# P1 row loop: next row's x loads issued behind the current row's stores (software prefetch into spare registers)
# baseline (speedup 1.0000x reference)
; #define GAS __attribute__((address_space(1)))
; #define LAS __attribute__((address_space(3)))
; template <int LO, int HI> __global__ void __launch_bounds__(NWAVES * 64, 2) fox_fwd(Args args) {
;     ...
;         LAS float* wf = (LAS float*)L;
;         for (int i = tid; i < 2048; i += NWAVES * 64) ((LAS f32x4*)wf)[i] = ((const f32x4*)WF)[i];
;         __syncthreads();
;         const int m0 = gw * 16, b = m0 / T;
;         f32x4 gm[4], sh[4];
; #pragma unroll
;         for (int j = 0; j < 4; ++j) { const int col = P1COL(j); const f32x4 g = *(const f32x4*)(norm_g + col), scl = *(const f32x4*)(ADA + b * 3072 + 1024 + col);
;             gm[j] = g * (scl + 1.0f); sh[j] = *(const f32x4*)(ADA + b * 3072 + col); }
;         const float bfv = b_f[lane & 7]; f32x4 lsq[4];
; #pragma unroll
;         for (int k = 0; k < 4; ++k) lsq[k] = (f32x4){0.f, 0.f, 0.f, 0.f};
;         for (int r = 0; r < 16; ++r) { const int m = m0 + r;
;             const GAS float* xr = (const GAS float*)(x + (size_t)m * D);
;             f32x4 v[4]; float s2 = 0.f;
; #pragma unroll
;             for (int j = 0; j < 4; ++j) { v[j] = *(const GAS f32x4*)(xr + P1COL(j)); s2 += (v[j][0] * v[j][0] + v[j][1] * v[j][1]) + (v[j][2] * v[j][2] + v[j][3] * v[j][3]); }
;             const float rstd = 1.0f / sqrtf(wave_sum(s2) * (1.0f / D) + EPS);
.LBB0_130:
	s_or_b64 exec, exec, s[8:9]
	s_ashr_i32 s43, s15, 6
	s_lshl_b32 s8, s14, 3
	s_add_i32 s33, s8, s43
	s_ashr_i32 s8, s33, 31
	s_lshr_b32 s8, s8, 24
	s_add_i32 s8, s33, s8
	s_ashr_i32 s44, s8, 8
	s_mul_i32 s8, s44, 0xc00
	s_ashr_i32 s9, s8, 31
	s_lshl_b64 s[8:9], s[8:9], 2
	s_add_u32 s8, s26, s8
	s_addc_u32 s9, s27, s9
	s_add_u32 s10, s8, 0x1000
	s_addc_u32 s11, s9, 0
	s_lshl_b32 s28, s33, 4
	s_ashr_i32 s29, s28, 31
	s_lshl_b64 s[12:13], s[28:29], 12
	v_and_b32_e32 v1, 63, v34
	s_waitcnt lgkmcnt(0)
	s_add_u32 s30, s6, s12
	v_lshlrev_b32_e32 v54, 5, v1
	s_addc_u32 s31, s7, s13
	s_barrier
	global_load_dwordx4 v[26:29], v54, s[30:31]
	global_load_dwordx4 v[18:21], v54, s[30:31] offset:16
	global_load_dwordx4 v[22:25], v54, s[30:31] offset:2064
	global_load_dwordx4 v[30:33], v54, s[30:31] offset:2048
	global_load_dwordx4 v[38:41], v54, s[10:11] offset:16
	global_load_dwordx4 v[42:45], v54, s[10:11]
	v_mbcnt_lo_u32_b32 v3, -1, 0
	v_and_b32_e32 v2, 7, v34
	v_mbcnt_hi_u32_b32 v35, -1, v3
	v_or_b32_e32 v3, 0x800, v54
	v_lshlrev_b32_e32 v2, 2, v2
	global_load_dwordx4 v[46:49], v3, s[10:11] offset:16
	global_load_dwordx4 v[50:53], v3, s[10:11]
	global_load_dwordx4 v[58:61], v54, s[20:21] offset:16
	global_load_dwordx4 v[62:65], v54, s[20:21]
	global_load_dwordx4 v[74:77], v54, s[20:21] offset:2064
	global_load_dwordx4 v[78:81], v54, s[20:21] offset:2048
	global_load_dword v71, v2, s[4:5]
	v_xor_b32_e32 v83, 16, v35
	v_and_b32_e32 v68, 64, v35
	v_mov_b32_e32 v37, 0
	v_lshlrev_b32_e32 v36, 4, v1
	v_xor_b32_e32 v4, 1, v35
	v_add_u32_e32 v87, 64, v68
	s_mov_b64 s[12:13], 0x2000000
	v_xor_b32_e32 v5, 2, v35
	v_lshl_add_u64 v[2:3], s[26:27], 0, v[36:37]
	v_cmp_lt_i32_e32 vcc, v4, v87
	v_lshl_add_u64 v[56:57], v[2:3], 0, s[12:13]
	v_xor_b32_e32 v55, 4, v35
	v_cndmask_b32_e32 v2, v35, v4, vcc
	v_cmp_lt_i32_e32 vcc, v5, v87
	v_lshlrev_b32_e32 v165, 2, v2
	v_xor_b32_e32 v73, 8, v35
	v_cndmask_b32_e32 v88, v35, v5, vcc
	global_load_dwordx4 v[2:5], v54, s[8:9] offset:16
	global_load_dwordx4 v[6:9], v54, s[8:9]
	v_lshlrev_b32_e32 v169, 2, v88
	v_cmp_lt_i32_e32 vcc, v55, v87
	v_xor_b32_e32 v86, 32, v35
	v_mov_b32_e32 v69, 0x358637bd
	v_cndmask_b32_e32 v55, v35, v55, vcc
	v_lshlrev_b32_e32 v168, 2, v55
	v_cmp_lt_i32_e32 vcc, v73, v87
	s_mov_b32 s45, 0xf800000
	v_mov_b32_e32 v70, 0x260
	v_cndmask_b32_e32 v73, v35, v73, vcc
	v_lshlrev_b32_e32 v167, 2, v73
	v_cmp_lt_i32_e32 vcc, v83, v87
	s_lshl_b64 s[34:35], s[28:29], 11
	v_add_u32_e32 v72, 0, v54
	s_or_b32 s36, s28, 1
	s_ashr_i32 s37, s36, 31
	v_cmp_eq_u32_e64 s[10:11], 4, v1
	v_cmp_eq_u32_e64 s[12:13], 5, v1
	v_cmp_eq_u32_e64 s[14:15], 6, v1
	v_cmp_eq_u32_e64 s[16:17], 7, v1
	s_mov_b32 s29, 0xbfb8aa3b
	s_mov_b32 s46, 0x7f800000
	s_mov_b32 s47, 0x33800000
	s_movk_i32 s48, 0x2000
	s_mov_b64 s[38:39], 0x2800
	s_mov_b64 s[40:41], 0x800
	s_waitcnt vmcnt(14)
	v_pk_mul_f32 v[10:11], v[28:29], v[28:29]
	v_pk_mul_f32 v[12:13], v[26:27], v[26:27]
	s_waitcnt vmcnt(13)
	v_pk_mul_f32 v[14:15], v[20:21], v[20:21]
	v_pk_mul_f32 v[16:17], v[18:19], v[18:19]
	v_pk_mov_b32 v[84:85], v[12:13], v[10:11] op_sel:[1,0]
	v_mov_b32_e32 v13, v11
	v_pk_mov_b32 v[10:11], v[16:17], v[14:15] op_sel:[1,0]
	v_mov_b32_e32 v17, v15
	s_waitcnt vmcnt(11)
	v_mul_f32_e32 v66, v31, v31
	v_mul_f32_e32 v82, v33, v33
	v_pk_add_f32 v[12:13], v[84:85], v[12:13]
	v_pk_add_f32 v[10:11], v[10:11], v[16:17]
	v_mul_f32_e32 v89, v22, v22
	v_mul_f32_e32 v90, v23, v23
	v_mul_f32_e32 v91, v24, v24
	v_mul_f32_e32 v92, v25, v25
	v_pk_fma_f32 v[14:15], v[30:31], v[30:31], v[66:67] op_sel_hi:[1,1,0]
	v_pk_fma_f32 v[66:67], v[32:33], v[32:33], v[82:83] op_sel_hi:[1,1,0]
	v_pk_add_f32 v[12:13], v[12:13], v[12:13] op_sel:[0,1] op_sel_hi:[1,0]
	v_pk_add_f32 v[10:11], v[10:11], v[10:11] op_sel:[0,1] op_sel_hi:[1,0]
	v_mov_b32_e32 v15, v91
	v_mov_b32_e32 v67, v92
	v_mov_b32_e32 v13, v89
	v_mov_b32_e32 v11, v90
	v_pk_add_f32 v[14:15], v[14:15], v[66:67]
	v_pk_add_f32 v[10:11], v[12:13], v[10:11]
	v_cndmask_b32_e32 v82, v35, v83, vcc
	v_pk_add_f32 v[10:11], v[10:11], v[14:15]
	v_lshlrev_b32_e32 v166, 2, v82
	v_add_f32_e32 v66, v10, v11
	global_load_dwordx4 v[10:13], v54, s[8:9] offset:2064
	global_load_dwordx4 v[14:17], v54, s[8:9] offset:2048
	ds_bpermute_b32 v67, v165, v66
	s_waitcnt vmcnt(12)
	v_pk_add_f32 v[82:83], v[38:39], 1.0 op_sel_hi:[1,0]
	v_cmp_lt_i32_e32 vcc, v86, v87
	s_waitcnt vmcnt(11)
	v_pk_add_f32 v[44:45], v[44:45], 1.0 op_sel_hi:[1,0]
	s_waitcnt vmcnt(9)
	v_pk_add_f32 v[52:53], v[52:53], 1.0 op_sel_hi:[1,0]
	s_waitcnt lgkmcnt(0)
	v_add_f32_e32 v66, v66, v67
	ds_bpermute_b32 v67, v169, v66
	v_pk_add_f32 v[42:43], v[42:43], 1.0 op_sel_hi:[1,0]
	v_pk_add_f32 v[50:51], v[50:51], 1.0 op_sel_hi:[1,0]
	v_pk_add_f32 v[84:85], v[48:49], 1.0 op_sel_hi:[1,0]
	s_waitcnt vmcnt(5)
	v_pk_mul_f32 v[48:49], v[78:79], v[50:51]
	s_waitcnt lgkmcnt(0)
	v_add_f32_e32 v55, v66, v67
	ds_bpermute_b32 v66, v168, v55
	v_cndmask_b32_e32 v67, v35, v86, vcc
	v_lshlrev_b32_e32 v164, 2, v67
	v_pk_add_f32 v[86:87], v[46:47], 1.0 op_sel_hi:[1,0]
	v_pk_mul_f32 v[50:51], v[76:77], v[84:85]
	s_waitcnt lgkmcnt(0)
	v_add_f32_e32 v55, v55, v66
	ds_bpermute_b32 v73, v167, v55
	v_pk_add_f32 v[66:67], v[40:41], 1.0 op_sel_hi:[1,0]
	v_pk_mul_f32 v[40:41], v[62:63], v[42:43]
	v_pk_mul_f32 v[42:43], v[60:61], v[66:67]
	v_cmp_eq_u32_e64 s[8:9], 3, v1
	s_waitcnt lgkmcnt(0)
	v_add_f32_e32 v38, v55, v73
	ds_bpermute_b32 v39, v166, v38
	s_waitcnt lgkmcnt(0)
	v_add_f32_e32 v46, v38, v39
	ds_bpermute_b32 v47, v164, v46
	v_pk_mul_f32 v[38:39], v[64:65], v[44:45]
	v_pk_mul_f32 v[44:45], v[58:59], v[82:83]
	s_waitcnt lgkmcnt(0)
; #define GAS __attribute__((address_space(1)))
; #define LAS __attribute__((address_space(3)))
; __device__ __forceinline__ unsigned pk2(float lo, float hi) { return pg8::cvt_pk_bf16(lo, hi); }
; template <int LO, int HI> __global__ void __launch_bounds__(NWAVES * 64, 2) fox_fwd(Args args) {
;     ...
;             const float rstd = 1.0f / sqrtf(wave_sum(s2) * (1.0f / D) + EPS);
; #pragma unroll
;             for (int j = 0; j < 4; ++j) v[j] = v[j] * rstd * gm[j] + sh[j];
; #pragma unroll
;             for (int j = 0; j < 2; ++j) { v4u o; o.x = pk2(v[2 * j][0], v[2 * j][1]); o.y = pk2(v[2 * j][2], v[2 * j][3]); o.z = pk2(v[2 * j + 1][0], v[2 * j + 1][1]); o.w = pk2(v[2 * j + 1][2], v[2 * j + 1][3]);
;                 *(GAS v4u*)(HB + (size_t)m * D + 8 * lane + 512 * j) = o; }
;             float fl[8];
; #pragma unroll
;             for (int q = 0; q < 8; ++q) { float a = 0.f;
; #pragma unroll
;                 for (int j = 0; j < 4; ++j) { const f32x4 w = *(const LAS f32x4*)(wf + q * 1024 + P1COL(j)); a += (v[j][0] * w[0] + v[j][1] * w[1]) + (v[j][2] * w[2] + v[j][3] * w[3]); }
;                 fl[q] = wave_sum(a); }
	v_add_f32_e32 v46, v46, v47
	v_fmamk_f32 v46, v46, 0x3a800000, v69
	v_mul_f32_e32 v47, 0x4f800000, v46
	v_cmp_gt_f32_e32 vcc, s45, v46
	s_nop 1
	v_cndmask_b32_e32 v55, v46, v47, vcc
	v_sqrt_f32_e32 v58, v55
	v_pk_mul_f32 v[46:47], v[80:81], v[52:53]
	v_add_u32_e32 v52, -1, v58
	v_add_u32_e32 v53, 1, v58
	v_fma_f32 v59, -v52, v58, v55
	v_fma_f32 v60, -v53, v58, v55
	v_cmp_ge_f32_e64 s[4:5], 0, v59
	s_nop 1
	v_cndmask_b32_e64 v52, v58, v52, s[4:5]
	v_cmp_lt_f32_e64 s[4:5], 0, v60
	s_nop 1
	v_cndmask_b32_e64 v52, v52, v53, s[4:5]
	v_mul_f32_e32 v53, 0x37800000, v52
	v_cndmask_b32_e32 v52, v52, v53, vcc
	v_cmp_class_f32_e32 vcc, v55, v70
	s_nop 1
	v_cndmask_b32_e32 v55, v52, v55, vcc
	v_div_scale_f32 v58, s[4:5], v55, v55, 1.0
	v_rcp_f32_e32 v59, v58
	v_div_scale_f32 v60, vcc, 1.0, v55, 1.0
	v_pk_mul_f32 v[52:53], v[74:75], v[86:87]
	v_fma_f32 v61, -v58, v59, 1.0
	v_fmac_f32_e32 v59, v61, v59
	v_mul_f32_e32 v61, v60, v59
	v_fma_f32 v62, -v58, v61, v60
	v_fmac_f32_e32 v61, v62, v59
	v_fma_f32 v58, -v58, v61, v60
	v_div_fmas_f32 v58, v58, v59, v61
	v_div_fixup_f32 v64, v58, v55, 1.0
	v_pk_mul_f32 v[18:19], v[64:65], v[18:19] op_sel_hi:[0,1]
	v_pk_mul_f32 v[20:21], v[64:65], v[20:21] op_sel_hi:[0,1]
	s_waitcnt vmcnt(3)
	v_pk_fma_f32 v[60:61], v[42:43], v[20:21], v[4:5]
	v_pk_fma_f32 v[62:63], v[44:45], v[18:19], v[2:3]
	v_pk_mul_f32 v[18:19], v[64:65], v[30:31] op_sel_hi:[0,1]
	v_pk_mul_f32 v[20:21], v[64:65], v[32:33] op_sel_hi:[0,1]
	v_pk_mul_f32 v[58:59], v[64:65], v[26:27] op_sel_hi:[0,1]
	v_pk_mul_f32 v[26:27], v[64:65], v[28:29] op_sel_hi:[0,1]
	s_waitcnt vmcnt(0)
	v_pk_fma_f32 v[28:29], v[46:47], v[20:21], v[16:17]
	v_pk_fma_f32 v[30:31], v[48:49], v[18:19], v[14:15]
	v_pk_mul_f32 v[18:19], v[64:65], v[22:23] op_sel_hi:[0,1]
	v_pk_mul_f32 v[20:21], v[64:65], v[24:25] op_sel_hi:[0,1]
	v_pk_fma_f32 v[26:27], v[38:39], v[26:27], v[8:9]
	v_pk_fma_f32 v[58:59], v[40:41], v[58:59], v[6:7]
	v_pk_fma_f32 v[22:23], v[50:51], v[20:21], v[12:13]
	v_pk_fma_f32 v[24:25], v[52:53], v[18:19], v[10:11]
	v_lshl_add_u64 v[32:33], v[56:57], 0, s[34:35]
	v_cvt_pk_bf16_f32 v18, v58, v59
	v_cvt_pk_bf16_f32 v19, v26, v27
	v_cvt_pk_bf16_f32 v20, v62, v63
	v_cvt_pk_bf16_f32 v21, v60, v61
	global_store_dwordx4 v[32:33], v[18:21], off
	s_lshl_b64 s[4:5], s[36:37], 12
	s_add_u32 s4, s6, s4
	v_cvt_pk_bf16_f32 v18, v30, v31
	v_cvt_pk_bf16_f32 v19, v28, v29
	v_cvt_pk_bf16_f32 v20, v24, v25
	v_cvt_pk_bf16_f32 v21, v22, v23
	ds_read_b128 v[64:67], v72
	ds_read_b128 v[74:77], v72 offset:16
	global_store_dwordx4 v[32:33], v[18:21], off offset:1024
	ds_read_b128 v[18:21], v72 offset:12288
	s_addc_u32 s5, s7, s5
	s_waitcnt lgkmcnt(2)
	v_mul_f32_e32 v55, v59, v65
	v_fmac_f32_e32 v55, v58, v64
	v_mul_f32_e32 v64, v27, v67
	v_fmac_f32_e32 v64, v26, v66
	v_add_f32_e32 v55, v55, v64
	ds_read_b128 v[64:67], v72 offset:2048
	s_waitcnt lgkmcnt(2)
	v_mul_f32_e32 v73, v63, v75
	v_fmac_f32_e32 v73, v62, v74
	v_mul_f32_e32 v74, v61, v77
	v_fmac_f32_e32 v74, v60, v76
	v_add_f32_e32 v73, v73, v74
	ds_read_b128 v[74:77], v72 offset:2064
	s_waitcnt lgkmcnt(1)
	v_mul_f32_e32 v65, v31, v65
	v_fmac_f32_e32 v65, v30, v64
	v_mul_f32_e32 v64, v29, v67
	v_add_f32_e32 v55, 0, v55
	v_fmac_f32_e32 v64, v28, v66
	v_add_f32_e32 v55, v55, v73
	v_add_f32_e32 v64, v65, v64
	v_add_f32_e32 v55, v55, v64
	s_waitcnt lgkmcnt(0)
	v_mul_f32_e32 v64, v25, v75
	v_mul_f32_e32 v65, v23, v77
	v_fmac_f32_e32 v64, v24, v74
	v_fmac_f32_e32 v65, v22, v76
	v_add_f32_e32 v64, v64, v65
	v_add_f32_e32 v55, v55, v64
	ds_bpermute_b32 v64, v165, v55
	ds_read_b128 v[74:77], v72 offset:4112
	v_cmp_eq_u32_e64 s[6:7], 2, v1
	s_waitcnt lgkmcnt(1)
	v_add_f32_e32 v55, v55, v64
	ds_bpermute_b32 v64, v169, v55
	s_waitcnt lgkmcnt(1)
	v_mul_f32_e32 v75, v63, v75
	v_fmac_f32_e32 v75, v62, v74
	v_mul_f32_e32 v74, v61, v77
	v_fmac_f32_e32 v74, v60, v76
	s_waitcnt lgkmcnt(0)
	v_add_f32_e32 v55, v55, v64
	ds_read_b128 v[64:67], v72 offset:4096
	v_add_f32_e32 v74, v75, v74
	ds_bpermute_b32 v73, v168, v55
	s_waitcnt lgkmcnt(1)
	v_mul_f32_e32 v65, v59, v65
	v_fmac_f32_e32 v65, v58, v64
	v_mul_f32_e32 v64, v27, v67
	v_fmac_f32_e32 v64, v26, v66
	v_add_f32_e32 v64, v65, v64
	v_add_f32_e32 v78, 0, v64
	ds_read_b128 v[64:67], v72 offset:6144
	v_add_f32_e32 v78, v78, v74
	ds_read_b128 v[74:77], v72 offset:6160
	s_waitcnt lgkmcnt(2)
	v_add_f32_e32 v55, v55, v73
	ds_bpermute_b32 v73, v167, v55
	s_waitcnt lgkmcnt(2)
	v_mul_f32_e32 v65, v31, v65
	v_fmac_f32_e32 v65, v30, v64
	v_mul_f32_e32 v64, v29, v67
	v_fmac_f32_e32 v64, v28, v66
	v_add_f32_e32 v64, v65, v64
	s_waitcnt lgkmcnt(1)
	v_mul_f32_e32 v65, v25, v75
	v_mul_f32_e32 v66, v23, v77
	v_fmac_f32_e32 v65, v24, v74
	v_fmac_f32_e32 v66, v22, v76
	v_add_f32_e32 v64, v78, v64
	v_add_f32_e32 v65, v65, v66
	v_add_f32_e32 v64, v64, v65
	ds_bpermute_b32 v65, v165, v64
	s_waitcnt lgkmcnt(1)
	v_add_f32_e32 v55, v55, v73
	ds_bpermute_b32 v74, v166, v55
	v_lshlrev_b32_e32 v73, 3, v1
	s_waitcnt lgkmcnt(1)
	v_add_f32_e32 v75, v64, v65
	ds_bpermute_b32 v76, v169, v75
	ds_read_b128 v[64:67], v72 offset:8192
	s_waitcnt lgkmcnt(2)
	v_add_f32_e32 v55, v55, v74
	s_waitcnt lgkmcnt(1)
	v_add_f32_e32 v78, v75, v76
	ds_read_b128 v[74:77], v72 offset:8208
	s_waitcnt lgkmcnt(1)
	v_mul_f32_e32 v65, v59, v65
	v_fmac_f32_e32 v65, v58, v64
	v_mul_f32_e32 v64, v27, v67
	v_fmac_f32_e32 v64, v26, v66
	v_add_f32_e32 v64, v65, v64
	s_waitcnt lgkmcnt(0)
	v_mul_f32_e32 v75, v63, v75
	v_add_f32_e32 v80, 0, v64
	v_fmac_f32_e32 v75, v62, v74
	v_mul_f32_e32 v74, v61, v77
	ds_read_b128 v[64:67], v72 offset:10240
	v_fmac_f32_e32 v74, v60, v76
	v_add_f32_e32 v74, v75, v74
	v_add_f32_e32 v80, v80, v74
	ds_read_b128 v[74:77], v72 offset:10256
	s_waitcnt lgkmcnt(1)
; #define GAS __attribute__((address_space(1)))
; #define LAS __attribute__((address_space(3)))
; template <int LO, int HI> __global__ void __launch_bounds__(NWAVES * 64, 2) fox_fwd(Args args) {
;     ...
;         for (int r = 0; r < 16; ++r) { const int m = m0 + r;
;             const GAS float* xr = (const GAS float*)(x + (size_t)m * D);
;             f32x4 v[4]; float s2 = 0.f;
; #pragma unroll
;             for (int j = 0; j < 4; ++j) { v[j] = *(const GAS f32x4*)(xr + P1COL(j)); s2 += (v[j][0] * v[j][0] + v[j][1] * v[j][1]) + (v[j][2] * v[j][2] + v[j][3] * v[j][3]); }
;     ...
;             float fl[8];
; #pragma unroll
;             for (int q = 0; q < 8; ++q) { float a = 0.f;
; #pragma unroll
;                 for (int j = 0; j < 4; ++j) { const f32x4 w = *(const LAS f32x4*)(wf + q * 1024 + P1COL(j)); a += (v[j][0] * w[0] + v[j][1] * w[1]) + (v[j][2] * w[2] + v[j][3] * w[3]); }
;                 fl[q] = wave_sum(a); }
	v_mul_f32_e32 v65, v31, v65
	ds_bpermute_b32 v79, v168, v78
	v_fmac_f32_e32 v65, v30, v64
	v_mul_f32_e32 v64, v29, v67
	v_fmac_f32_e32 v64, v28, v66
	v_add_f32_e32 v64, v65, v64
	s_waitcnt lgkmcnt(1)
	v_mul_f32_e32 v65, v25, v75
	v_mul_f32_e32 v66, v23, v77
	v_fmac_f32_e32 v65, v24, v74
	v_fmac_f32_e32 v66, v22, v76
	v_add_f32_e32 v64, v80, v64
	v_add_f32_e32 v65, v65, v66
	v_add_f32_e32 v64, v64, v65
	s_waitcnt lgkmcnt(0)
	v_add_f32_e32 v67, v78, v79
	ds_bpermute_b32 v65, v165, v64
	ds_bpermute_b32 v66, v164, v55
	ds_bpermute_b32 v74, v167, v67
	s_waitcnt lgkmcnt(2)
	v_add_f32_e32 v32, v64, v65
	s_waitcnt lgkmcnt(1)
	v_add_f32_e32 v55, v55, v66
	s_waitcnt lgkmcnt(0)
	v_add_f32_e32 v74, v67, v74
	ds_read_b128 v[64:67], v72 offset:12304
	v_mul_f32_e32 v19, v59, v19
	v_fmac_f32_e32 v19, v58, v18
	v_mul_f32_e32 v18, v27, v21
	v_fmac_f32_e32 v18, v26, v20
	v_add_f32_e32 v18, v19, v18
	s_waitcnt lgkmcnt(0)
	v_mul_f32_e32 v65, v63, v65
	v_add_f32_e32 v76, 0, v18
	v_fmac_f32_e32 v65, v62, v64
	v_mul_f32_e32 v64, v61, v67
	ds_read_b128 v[18:21], v72 offset:14336
	v_fmac_f32_e32 v64, v60, v66
	v_add_f32_e32 v64, v65, v64
	v_add_f32_e32 v76, v76, v64
	ds_read_b128 v[64:67], v72 offset:14352
	s_waitcnt lgkmcnt(1)
	v_mul_f32_e32 v19, v31, v19
	v_fmac_f32_e32 v19, v30, v18
	v_mul_f32_e32 v18, v29, v21
	v_fmac_f32_e32 v18, v28, v20
	v_add_f32_e32 v18, v19, v18
	s_waitcnt lgkmcnt(0)
	v_mul_f32_e32 v19, v25, v65
	v_mul_f32_e32 v20, v23, v67
	v_fmac_f32_e32 v19, v24, v64
	v_fmac_f32_e32 v20, v22, v66
	v_add_f32_e32 v18, v76, v18
	v_add_f32_e32 v19, v19, v20
	v_add_f32_e32 v64, v18, v19
	ds_bpermute_b32 v75, v166, v74
	ds_bpermute_b32 v65, v165, v64
	ds_read_b128 v[18:21], v72 offset:16384
	ds_bpermute_b32 v33, v169, v32
	s_waitcnt lgkmcnt(3)
	v_add_f32_e32 v74, v74, v75
	s_waitcnt lgkmcnt(2)
	v_add_f32_e32 v75, v64, v65
	ds_read_b128 v[64:67], v72 offset:16400
	s_waitcnt lgkmcnt(2)
	v_mul_f32_e32 v19, v59, v19
	v_fmac_f32_e32 v19, v58, v18
	v_mul_f32_e32 v18, v27, v21
	v_fmac_f32_e32 v18, v26, v20
	v_add_f32_e32 v18, v19, v18
	s_waitcnt lgkmcnt(0)
	v_mul_f32_e32 v65, v63, v65
	v_add_f32_e32 v77, 0, v18
	v_fmac_f32_e32 v65, v62, v64
	v_mul_f32_e32 v64, v61, v67
	ds_read_b128 v[18:21], v72 offset:18432
	v_fmac_f32_e32 v64, v60, v66
	v_add_f32_e32 v64, v65, v64
	v_add_f32_e32 v32, v32, v33
	v_add_f32_e32 v77, v77, v64
	ds_read_b128 v[64:67], v72 offset:18448
	ds_bpermute_b32 v33, v168, v32
	s_waitcnt lgkmcnt(2)
	v_mul_f32_e32 v19, v31, v19
	v_fmac_f32_e32 v19, v30, v18
	v_mul_f32_e32 v18, v29, v21
	v_fmac_f32_e32 v18, v28, v20
	v_add_f32_e32 v18, v19, v18
	s_waitcnt lgkmcnt(1)
	v_mul_f32_e32 v19, v25, v65
	v_mul_f32_e32 v20, v23, v67
	s_waitcnt lgkmcnt(0)
	v_add_f32_e32 v32, v32, v33
	ds_bpermute_b32 v76, v169, v75
	v_fmac_f32_e32 v19, v24, v64
	v_fmac_f32_e32 v20, v22, v66
	ds_bpermute_b32 v33, v167, v32
	v_add_f32_e32 v18, v77, v18
	v_add_f32_e32 v19, v19, v20
	v_add_f32_e32 v18, v18, v19
	ds_bpermute_b32 v19, v165, v18
	s_waitcnt lgkmcnt(2)
	v_add_f32_e32 v21, v75, v76
	s_waitcnt lgkmcnt(1)
	v_add_f32_e32 v20, v32, v33
	ds_bpermute_b32 v32, v168, v21
	ds_bpermute_b32 v33, v166, v20
	s_waitcnt lgkmcnt(2)
	v_add_f32_e32 v18, v18, v19
	ds_bpermute_b32 v19, v169, v18
	ds_bpermute_b32 v64, v164, v74
	s_waitcnt lgkmcnt(3)
	v_add_f32_e32 v21, v21, v32
	ds_bpermute_b32 v32, v167, v21
	s_waitcnt lgkmcnt(3)
	v_add_f32_e32 v20, v20, v33
	s_waitcnt lgkmcnt(2)
	v_add_f32_e32 v18, v18, v19
	ds_bpermute_b32 v19, v168, v18
	ds_bpermute_b32 v33, v164, v20
	s_waitcnt lgkmcnt(2)
	v_add_f32_e32 v21, v21, v32
	ds_bpermute_b32 v32, v166, v21
	v_add_f32_e32 v74, v74, v64
	s_waitcnt lgkmcnt(2)
	v_add_f32_e32 v64, v18, v19
	ds_bpermute_b32 v65, v167, v64
	s_waitcnt lgkmcnt(2)
	v_add_f32_e32 v75, v20, v33
	s_waitcnt lgkmcnt(1)
	v_add_f32_e32 v32, v21, v32
	ds_read_b128 v[18:21], v72 offset:20480
	ds_bpermute_b32 v33, v164, v32
	s_waitcnt lgkmcnt(2)
	v_add_f32_e32 v76, v64, v65
	ds_read_b128 v[64:67], v72 offset:20496
	ds_bpermute_b32 v77, v166, v76
	s_waitcnt lgkmcnt(3)
	v_mul_f32_e32 v19, v59, v19
	v_fmac_f32_e32 v19, v58, v18
	v_mul_f32_e32 v18, v27, v21
	v_fmac_f32_e32 v18, v26, v20
	v_add_f32_e32 v18, v19, v18
	s_waitcnt lgkmcnt(1)
	v_mul_f32_e32 v65, v63, v65
	v_add_f32_e32 v78, 0, v18
	v_fmac_f32_e32 v65, v62, v64
	v_mul_f32_e32 v64, v61, v67
	ds_read_b128 v[18:21], v72 offset:22528
	v_fmac_f32_e32 v64, v60, v66
	v_add_f32_e32 v64, v65, v64
	v_add_f32_e32 v78, v78, v64
	ds_read_b128 v[64:67], v72 offset:22544
	s_waitcnt lgkmcnt(1)
	v_mul_f32_e32 v19, v31, v19
	v_fmac_f32_e32 v19, v30, v18
	v_mul_f32_e32 v18, v29, v21
	v_fmac_f32_e32 v18, v28, v20
	v_add_f32_e32 v18, v19, v18
	s_waitcnt lgkmcnt(0)
	v_mul_f32_e32 v19, v25, v65
	v_mul_f32_e32 v20, v23, v67
	v_fmac_f32_e32 v19, v24, v64
	v_fmac_f32_e32 v20, v22, v66
	v_add_f32_e32 v18, v78, v18
	v_add_f32_e32 v19, v19, v20
	v_add_f32_e32 v64, v18, v19
	ds_bpermute_b32 v65, v165, v64
	ds_read_b128 v[18:21], v72 offset:24576
	v_add_f32_e32 v92, v32, v33
	v_add_f32_e32 v93, v76, v77
	ds_bpermute_b32 v94, v164, v93
	s_waitcnt lgkmcnt(2)
	v_add_f32_e32 v95, v64, v65
	ds_read_b128 v[64:67], v72 offset:24592
	s_waitcnt lgkmcnt(2)
	v_pk_mul_f32 v[18:19], v[58:59], v[18:19]
	v_pk_mul_f32 v[20:21], v[26:27], v[20:21]
	ds_bpermute_b32 v96, v169, v95
	v_pk_mov_b32 v[32:33], v[18:19], v[20:21] op_sel:[1,0]
	v_mov_b32_e32 v19, v21
	v_pk_add_f32 v[18:19], v[32:33], v[18:19]
	s_waitcnt lgkmcnt(1)
	v_pk_mul_f32 v[64:65], v[62:63], v[64:65]
	v_add_f32_e32 v18, v18, v19
	v_add_f32_e32 v32, 0, v18
	ds_read_b128 v[18:21], v72 offset:26624
	ds_read_b128 v[76:79], v72 offset:26640
	global_load_dwordx4 v[80:83], v54, s[4:5] offset:16
	global_load_dwordx4 v[84:87], v54, s[4:5]
	v_pk_mul_f32 v[66:67], v[60:61], v[66:67]
	s_waitcnt lgkmcnt(0)
; #define GAS __attribute__((address_space(1)))
; #define LAS __attribute__((address_space(3)))
; template <int LO, int HI> __global__ void __launch_bounds__(NWAVES * 64, 2) fox_fwd(Args args) {
;     ...
;             for (int j = 0; j < 4; ++j) { v[j] = *(const GAS f32x4*)(xr + P1COL(j)); s2 += (v[j][0] * v[j][0] + v[j][1] * v[j][1]) + (v[j][2] * v[j][2] + v[j][3] * v[j][3]); }
;             const float rstd = 1.0f / sqrtf(wave_sum(s2) * (1.0f / D) + EPS);
;     ...
;             for (int q = 0; q < 8; ++q) { float a = 0.f;
; #pragma unroll
;                 for (int j = 0; j < 4; ++j) { const f32x4 w = *(const LAS f32x4*)(wf + q * 1024 + P1COL(j)); a += (v[j][0] * w[0] + v[j][1] * w[1]) + (v[j][2] * w[2] + v[j][3] * w[3]); }
;                 fl[q] = wave_sum(a); }
;             float mine = fl[0];
; #pragma unroll
;             for (int q = 1; q < 8; ++q) mine = (lane == q) ? fl[q] : mine;
;             { const float z = mine + bfv; const float ls = fminf(z, 0.f) - log1pf(__expf(-fabsf(z)));
	v_mul_f32_e32 v33, v24, v76
	v_pk_mov_b32 v[88:89], v[64:65], v[66:67] op_sel:[1,0]
	v_mov_b32_e32 v65, v67
	v_pk_add_f32 v[64:65], v[88:89], v[64:65]
	v_mul_f32_e32 v66, v25, v77
	v_mul_f32_e32 v67, v22, v78
	v_mul_f32_e32 v97, v23, v79
	global_load_dwordx4 v[76:79], v54, s[4:5] offset:2048
	global_load_dwordx4 v[88:91], v54, s[4:5] offset:2064
	v_pk_add_f32 v[64:65], v[64:65], v[64:65] op_sel:[0,1] op_sel_hi:[1,0]
	v_cmp_eq_u32_e64 s[4:5], 1, v1
	v_mov_b32_e32 v65, v66
	v_pk_add_f32 v[32:33], v[32:33], v[64:65]
	v_mul_f32_e32 v64, v31, v19
	v_pk_fma_f32 v[18:19], v[30:31], v[18:19], v[64:65] op_sel_hi:[1,1,0]
	v_mul_f32_e32 v64, v29, v21
	v_pk_fma_f32 v[20:21], v[28:29], v[20:21], v[64:65] op_sel_hi:[1,1,0]
	v_mov_b32_e32 v19, v67
	v_mov_b32_e32 v21, v97
	v_pk_add_f32 v[64:65], v[18:19], v[20:21]
	ds_read_b128 v[18:21], v72 offset:28672
	v_pk_add_f32 v[32:33], v[32:33], v[64:65]
	ds_read_b128 v[64:67], v72 offset:28688
	v_add_f32_e32 v97, v32, v33
	ds_bpermute_b32 v98, v165, v97
	s_waitcnt lgkmcnt(2)
	v_pk_mul_f32 v[18:19], v[58:59], v[18:19]
	v_pk_mul_f32 v[20:21], v[26:27], v[20:21]
	s_waitcnt lgkmcnt(1)
	v_pk_mul_f32 v[32:33], v[62:63], v[64:65]
	v_pk_mov_b32 v[26:27], v[18:19], v[20:21] op_sel:[1,0]
	v_mov_b32_e32 v19, v21
	v_pk_add_f32 v[18:19], v[26:27], v[18:19]
	v_pk_mul_f32 v[58:59], v[60:61], v[66:67]
	v_add_f32_e32 v18, v18, v19
	v_add_f32_e32 v26, 0, v18
	ds_read_b128 v[18:21], v72 offset:30720
	ds_read_b128 v[62:65], v72 offset:30736
	v_pk_mov_b32 v[60:61], v[32:33], v[58:59] op_sel:[1,0]
	v_mov_b32_e32 v33, v59
	v_pk_add_f32 v[32:33], v[60:61], v[32:33]
	s_waitcnt lgkmcnt(0)
	v_mul_f32_e32 v27, v24, v62
	v_mul_f32_e32 v24, v25, v63
	v_mul_f32_e32 v25, v22, v64
	v_mul_f32_e32 v58, v23, v65
	v_pk_add_f32 v[22:23], v[32:33], v[32:33] op_sel:[0,1] op_sel_hi:[1,0]
	s_nop 0
	v_mov_b32_e32 v23, v24
	v_mul_f32_e32 v24, v31, v19
	v_pk_fma_f32 v[18:19], v[30:31], v[18:19], v[24:25] op_sel_hi:[1,1,0]
	v_mul_f32_e32 v24, v29, v21
	v_pk_fma_f32 v[20:21], v[28:29], v[20:21], v[24:25] op_sel_hi:[1,1,0]
	v_mov_b32_e32 v19, v25
	v_mov_b32_e32 v21, v58
	v_pk_add_f32 v[22:23], v[26:27], v[22:23]
	v_pk_add_f32 v[18:19], v[18:19], v[20:21]
	v_add_f32_e32 v20, v95, v96
	v_pk_add_f32 v[18:19], v[22:23], v[18:19]
	ds_bpermute_b32 v21, v168, v20
	v_add_f32_e32 v18, v18, v19
	ds_bpermute_b32 v19, v165, v18
	v_add_f32_e32 v22, v97, v98
	ds_bpermute_b32 v23, v169, v22
	s_waitcnt lgkmcnt(2)
	v_add_f32_e32 v20, v20, v21
	ds_bpermute_b32 v21, v167, v20
	s_waitcnt lgkmcnt(2)
	v_add_f32_e32 v18, v18, v19
	ds_bpermute_b32 v19, v169, v18
	s_waitcnt lgkmcnt(2)
	v_add_f32_e32 v22, v22, v23
	ds_bpermute_b32 v23, v168, v22
	s_waitcnt lgkmcnt(2)
	v_add_f32_e32 v20, v20, v21
	ds_bpermute_b32 v21, v166, v20
	s_waitcnt lgkmcnt(2)
	v_add_f32_e32 v18, v18, v19
	ds_bpermute_b32 v19, v168, v18
	s_waitcnt lgkmcnt(2)
	v_add_f32_e32 v22, v22, v23
	ds_bpermute_b32 v23, v167, v22
	s_waitcnt lgkmcnt(2)
	v_add_f32_e32 v26, v20, v21
	ds_bpermute_b32 v27, v164, v26
	s_waitcnt lgkmcnt(2)
	v_add_f32_e32 v18, v18, v19
	ds_bpermute_b32 v19, v167, v18
	s_waitcnt vmcnt(2)
	v_pk_mul_f32 v[20:21], v[84:85], v[84:85]
	s_waitcnt lgkmcnt(2)
	v_add_f32_e32 v28, v22, v23
	ds_bpermute_b32 v29, v166, v28
	s_waitcnt lgkmcnt(1)
	v_add_f32_e32 v30, v18, v19
	v_pk_mul_f32 v[18:19], v[86:87], v[86:87]
	ds_bpermute_b32 v31, v166, v30
	v_pk_mov_b32 v[22:23], v[20:21], v[18:19] op_sel:[1,0]
	v_mov_b32_e32 v21, v19
	v_pk_add_f32 v[18:19], v[22:23], v[20:21]
	v_pk_mul_f32 v[20:21], v[82:83], v[82:83]
	v_pk_mul_f32 v[22:23], v[80:81], v[80:81]
	v_pk_add_f32 v[18:19], v[18:19], v[18:19] op_sel:[0,1] op_sel_hi:[1,0]
	v_pk_mov_b32 v[24:25], v[22:23], v[20:21] op_sel:[1,0]
	v_mov_b32_e32 v23, v21
	v_pk_add_f32 v[20:21], v[24:25], v[22:23]
	s_waitcnt vmcnt(0)
	v_mul_f32_e32 v22, v88, v88
	v_mul_f32_e32 v23, v89, v89
	v_pk_add_f32 v[20:21], v[20:21], v[20:21] op_sel:[0,1] op_sel_hi:[1,0]
	v_mov_b32_e32 v19, v22
	v_mov_b32_e32 v21, v23
	v_pk_add_f32 v[18:19], v[18:19], v[20:21]
	v_mul_f32_e32 v20, v77, v77
	v_mul_f32_e32 v22, v79, v79
	v_mul_f32_e32 v24, v90, v90
	v_mul_f32_e32 v25, v91, v91
	v_pk_fma_f32 v[20:21], v[76:77], v[76:77], v[20:21] op_sel_hi:[1,1,0]
	v_pk_fma_f32 v[22:23], v[78:79], v[78:79], v[22:23] op_sel_hi:[1,1,0]
	v_mov_b32_e32 v21, v24
	v_mov_b32_e32 v23, v25
	v_pk_add_f32 v[20:21], v[20:21], v[22:23]
	s_waitcnt lgkmcnt(0)
	v_add_f32_e32 v22, v30, v31
	v_pk_add_f32 v[18:19], v[18:19], v[20:21]
	v_add_f32_e32 v20, v28, v29
	v_add_f32_e32 v18, v18, v19
	ds_bpermute_b32 v19, v165, v18
	ds_bpermute_b32 v21, v164, v20
	ds_bpermute_b32 v23, v164, v22
	v_add_f32_e32 v24, v93, v94
	v_add_f32_e32 v25, v26, v27
	s_waitcnt lgkmcnt(2)
	v_add_f32_e32 v18, v18, v19
	ds_bpermute_b32 v19, v169, v18
	s_waitcnt lgkmcnt(2)
	v_add_f32_e32 v20, v20, v21
	s_waitcnt lgkmcnt(1)
	v_add_f32_e32 v21, v22, v23
	v_cndmask_b32_e64 v22, v55, v74, s[4:5]
	v_cndmask_b32_e64 v22, v22, v75, s[6:7]
	s_waitcnt lgkmcnt(0)
	v_add_f32_e32 v18, v18, v19
	ds_bpermute_b32 v19, v168, v18
	v_cndmask_b32_e64 v22, v22, v92, s[8:9]
	v_cndmask_b32_e64 v22, v22, v24, s[10:11]
	v_cndmask_b32_e64 v22, v22, v25, s[12:13]
	v_cndmask_b32_e64 v20, v22, v20, s[14:15]
	s_waitcnt lgkmcnt(0)
	v_add_f32_e32 v18, v18, v19
	ds_bpermute_b32 v19, v167, v18
	v_cndmask_b32_e64 v20, v20, v21, s[16:17]
	v_add_f32_e32 v20, v71, v20
	v_min_f32_e32 v22, 0, v20
	v_mul_f32_e64 v20, |v20|, s29
	s_waitcnt lgkmcnt(0)
	v_add_f32_e32 v18, v18, v19
	ds_bpermute_b32 v19, v166, v18
	v_exp_f32_e32 v55, v20
	s_waitcnt lgkmcnt(0)
	v_add_f32_e32 v18, v18, v19
	ds_bpermute_b32 v19, v164, v18
	v_add_f32_e32 v92, 1.0, v55
	v_add_f32_e32 v23, -1.0, v92
	v_sub_f32_e32 v26, v23, v92
	v_add_f32_e32 v26, 1.0, v26
	s_waitcnt lgkmcnt(0)
; #define GAS __attribute__((address_space(1)))
; #define LAS __attribute__((address_space(3)))
; __device__ __forceinline__ unsigned pk2(float lo, float hi) { return pg8::cvt_pk_bf16(lo, hi); }
; template <int LO, int HI> __global__ void __launch_bounds__(NWAVES * 64, 2) fox_fwd(Args args) {
;     ...
;             const float rstd = 1.0f / sqrtf(wave_sum(s2) * (1.0f / D) + EPS);
; #pragma unroll
;             for (int j = 0; j < 4; ++j) v[j] = v[j] * rstd * gm[j] + sh[j];
; #pragma unroll
;             for (int j = 0; j < 2; ++j) { v4u o; o.x = pk2(v[2 * j][0], v[2 * j][1]); o.y = pk2(v[2 * j][2], v[2 * j][3]); o.z = pk2(v[2 * j + 1][0], v[2 * j + 1][1]); o.w = pk2(v[2 * j + 1][2], v[2 * j + 1][3]);
;                 *(GAS v4u*)(HB + (size_t)m * D + 8 * lane + 512 * j) = o; }
;             float fl[8];
; #pragma unroll
;             for (int q = 0; q < 8; ++q) { float a = 0.f;
; #pragma unroll
;                 for (int j = 0; j < 4; ++j) { const f32x4 w = *(const LAS f32x4*)(wf + q * 1024 + P1COL(j)); a += (v[j][0] * w[0] + v[j][1] * w[1]) + (v[j][2] * w[2] + v[j][3] * w[3]); }
;                 fl[q] = wave_sum(a); }
	v_add_f32_e32 v18, v18, v19
	v_fmamk_f32 v18, v18, 0x3a800000, v69
	v_mul_f32_e32 v19, 0x4f800000, v18
	v_cmp_gt_f32_e32 vcc, s45, v18
	v_sub_f32_e32 v23, v55, v23
	v_add_f32_e32 v23, v23, v26
	v_cndmask_b32_e32 v18, v18, v19, vcc
	v_sqrt_f32_e32 v19, v18
	s_nop 0
	v_add_u32_e32 v20, -1, v19
	v_fma_f32 v21, -v20, v19, v18
	v_cmp_ge_f32_e64 s[20:21], 0, v21
	v_add_u32_e32 v21, 1, v19
	s_nop 0
	v_cndmask_b32_e64 v20, v19, v20, s[20:21]
	v_fma_f32 v19, -v21, v19, v18
	v_cmp_lt_f32_e64 s[20:21], 0, v19
	s_nop 1
	v_cndmask_b32_e64 v19, v20, v21, s[20:21]
	v_mul_f32_e32 v20, 0x37800000, v19
	v_cndmask_b32_e32 v19, v19, v20, vcc
	v_cmp_class_f32_e32 vcc, v18, v70
	s_nop 1
	v_cndmask_b32_e32 v18, v19, v18, vcc
	v_div_scale_f32 v19, s[20:21], v18, v18, 1.0
	v_rcp_f32_e32 v20, v19
	s_lshl_b64 s[20:21], s[36:37], 11
	s_mov_b32 s37, 0x3f2aaaab
	s_mov_b32 s36, 0x3f317218
	v_fma_f32 v21, -v19, v20, 1.0
	v_fmac_f32_e32 v20, v21, v20
	v_div_scale_f32 v21, vcc, 1.0, v18, 1.0
	v_mul_f32_e32 v24, v21, v20
	v_fma_f32 v25, -v19, v24, v21
	v_fmac_f32_e32 v24, v25, v20
	v_fma_f32 v19, -v19, v24, v21
	v_div_fmas_f32 v19, v19, v20, v24
	v_div_fixup_f32 v18, v19, v18, 1.0
	v_pk_mul_f32 v[20:21], v[18:19], v[84:85] op_sel_hi:[0,1]
	v_pk_mul_f32 v[24:25], v[18:19], v[86:87] op_sel_hi:[0,1]
	v_pk_fma_f32 v[64:65], v[40:41], v[20:21], v[6:7]
	v_pk_mul_f32 v[20:21], v[18:19], v[80:81] op_sel_hi:[0,1]
	v_pk_fma_f32 v[62:63], v[38:39], v[24:25], v[8:9]
	v_pk_mul_f32 v[24:25], v[18:19], v[82:83] op_sel_hi:[0,1]
	v_pk_fma_f32 v[66:67], v[44:45], v[20:21], v[2:3]
	v_pk_mul_f32 v[20:21], v[18:19], v[76:77] op_sel_hi:[0,1]
	v_pk_fma_f32 v[32:33], v[42:43], v[24:25], v[4:5]
	v_pk_mul_f32 v[24:25], v[18:19], v[78:79] op_sel_hi:[0,1]
	v_pk_fma_f32 v[30:31], v[48:49], v[20:21], v[14:15]
	v_pk_mul_f32 v[20:21], v[18:19], v[88:89] op_sel_hi:[0,1]
	v_pk_mul_f32 v[18:19], v[18:19], v[90:91] op_sel_hi:[0,1]
	v_pk_fma_f32 v[28:29], v[46:47], v[24:25], v[16:17]
	v_pk_fma_f32 v[58:59], v[50:51], v[18:19], v[12:13]
	v_pk_fma_f32 v[60:61], v[52:53], v[20:21], v[10:11]
	v_lshl_add_u64 v[24:25], v[56:57], 0, s[20:21]
	v_cvt_pk_bf16_f32 v18, v64, v65
	v_cvt_pk_bf16_f32 v19, v62, v63
	v_cvt_pk_bf16_f32 v20, v66, v67
	v_cvt_pk_bf16_f32 v21, v32, v33
	global_store_dwordx4 v[24:25], v[18:21], off
	s_mov_b32 s20, 0x3e9b6dac
	s_nop 0
	v_cvt_pk_bf16_f32 v18, v30, v31
	v_cvt_pk_bf16_f32 v19, v28, v29
	v_cvt_pk_bf16_f32 v20, v60, v61
	v_cvt_pk_bf16_f32 v21, v58, v59
	ds_read_b128 v[74:77], v72
	ds_read_b128 v[78:81], v72 offset:16
	s_waitcnt lgkmcnt(1)
	v_mul_f32_e32 v26, v65, v75
	v_mul_f32_e32 v27, v63, v77
	v_fmac_f32_e32 v26, v64, v74
	v_fmac_f32_e32 v27, v62, v76
	ds_read_b128 v[74:77], v72 offset:2048
	v_add_f32_e32 v26, v26, v27
	s_waitcnt lgkmcnt(1)
	v_mul_f32_e32 v27, v67, v79
	v_mul_f32_e32 v56, v33, v81
	v_fmac_f32_e32 v27, v66, v78
	v_fmac_f32_e32 v56, v32, v80
	ds_read_b128 v[78:81], v72 offset:2064
	v_add_f32_e32 v26, 0, v26
	v_add_f32_e32 v27, v27, v56
	v_add_f32_e32 v26, v26, v27
	s_waitcnt lgkmcnt(1)
	v_mul_f32_e32 v27, v31, v75
	v_mul_f32_e32 v56, v29, v77
	v_fmac_f32_e32 v27, v30, v74
	v_fmac_f32_e32 v56, v28, v76
	v_add_f32_e32 v27, v27, v56
	v_add_f32_e32 v26, v26, v27
	s_waitcnt lgkmcnt(0)
	v_mul_f32_e32 v27, v61, v79
	v_mul_f32_e32 v56, v59, v81
	v_fmac_f32_e32 v27, v60, v78
	v_fmac_f32_e32 v56, v58, v80
	v_add_f32_e32 v27, v27, v56
	v_add_f32_e32 v56, v26, v27
	ds_bpermute_b32 v57, v165, v56
	v_frexp_mant_f32_e32 v74, v92
	v_cmp_gt_f32_e32 vcc, s37, v74
	ds_read_b128 v[74:77], v72 offset:4096
	v_cvt_f64_f32_e32 v[26:27], v92
	s_waitcnt lgkmcnt(1)
	v_add_f32_e32 v57, v56, v57
	ds_bpermute_b32 v78, v169, v57
	v_frexp_exp_i32_f64_e32 v26, v[26:27]
	v_subbrev_co_u32_e32 v56, vcc, 0, v26, vcc
	v_sub_u32_e32 v27, 0, v56
	s_waitcnt lgkmcnt(0)
	v_add_f32_e32 v57, v57, v78
	ds_read_b128 v[78:81], v72 offset:4112
	v_mul_f32_e32 v26, v65, v75
	v_fmac_f32_e32 v26, v64, v74
	v_mul_f32_e32 v74, v63, v77
	v_fmac_f32_e32 v74, v62, v76
	v_add_f32_e32 v26, v26, v74
	s_waitcnt lgkmcnt(0)
	v_mul_f32_e32 v79, v67, v79
	ds_read_b128 v[74:77], v72 offset:6144
	v_fmac_f32_e32 v79, v66, v78
	v_mul_f32_e32 v78, v33, v81
	v_fmac_f32_e32 v78, v32, v80
	v_add_f32_e32 v26, 0, v26
	v_add_f32_e32 v78, v79, v78
	v_add_f32_e32 v26, v26, v78
	ds_read_b128 v[78:81], v72 offset:6160
	s_waitcnt lgkmcnt(1)
	v_mul_f32_e32 v75, v31, v75
	v_fmac_f32_e32 v75, v30, v74
	v_mul_f32_e32 v74, v29, v77
	v_fmac_f32_e32 v74, v28, v76
	v_add_f32_e32 v74, v75, v74
	v_add_f32_e32 v26, v26, v74
	s_waitcnt lgkmcnt(0)
	v_mul_f32_e32 v74, v61, v79
	v_mul_f32_e32 v75, v59, v81
	v_fmac_f32_e32 v74, v60, v78
	v_fmac_f32_e32 v75, v58, v80
	v_add_f32_e32 v74, v74, v75
	v_add_f32_e32 v78, v26, v74
	ds_bpermute_b32 v79, v165, v78
	ds_read_b128 v[74:77], v72 offset:8192
	ds_bpermute_b32 v82, v168, v57
	v_ldexp_f32 v26, v92, v27
	s_waitcnt lgkmcnt(2)
	v_add_f32_e32 v83, v78, v79
	ds_read_b128 v[78:81], v72 offset:8208
	s_waitcnt lgkmcnt(2)
	v_mul_f32_e32 v75, v65, v75
	v_fmac_f32_e32 v75, v64, v74
	v_mul_f32_e32 v74, v63, v77
	v_fmac_f32_e32 v74, v62, v76
	v_add_f32_e32 v74, v75, v74
	s_waitcnt lgkmcnt(0)
	v_mul_f32_e32 v79, v67, v79
	v_add_f32_e32 v85, 0, v74
	v_fmac_f32_e32 v79, v66, v78
	v_mul_f32_e32 v78, v33, v81
	ds_read_b128 v[74:77], v72 offset:10240
	v_fmac_f32_e32 v78, v32, v80
	v_add_f32_e32 v78, v79, v78
	v_add_f32_e32 v85, v85, v78
	ds_read_b128 v[78:81], v72 offset:10256
	s_waitcnt lgkmcnt(1)
	v_mul_f32_e32 v75, v31, v75
	v_fmac_f32_e32 v75, v30, v74
	v_mul_f32_e32 v74, v29, v77
	v_fmac_f32_e32 v74, v28, v76
	v_add_f32_e32 v57, v57, v82
	v_add_f32_e32 v74, v75, v74
	s_waitcnt lgkmcnt(0)
; #define LAS __attribute__((address_space(3)))
; template <int LO, int HI> __global__ void __launch_bounds__(NWAVES * 64, 2) fox_fwd(Args args) {
;     ...
;             float fl[8];
; #pragma unroll
;             for (int q = 0; q < 8; ++q) { float a = 0.f;
; #pragma unroll
;                 for (int j = 0; j < 4; ++j) { const f32x4 w = *(const LAS f32x4*)(wf + q * 1024 + P1COL(j)); a += (v[j][0] * w[0] + v[j][1] * w[1]) + (v[j][2] * w[2] + v[j][3] * w[3]); }
;                 fl[q] = wave_sum(a); }
	v_mul_f32_e32 v75, v61, v79
	v_mul_f32_e32 v76, v59, v81
	ds_bpermute_b32 v82, v167, v57
	v_fmac_f32_e32 v75, v60, v78
	v_fmac_f32_e32 v76, v58, v80
	v_add_f32_e32 v74, v85, v74
	v_add_f32_e32 v75, v75, v76
	v_add_f32_e32 v74, v74, v75
	ds_bpermute_b32 v84, v169, v83
	ds_bpermute_b32 v75, v165, v74
	s_waitcnt lgkmcnt(2)
	v_add_f32_e32 v57, v57, v82
	ds_bpermute_b32 v76, v166, v57
	s_waitcnt lgkmcnt(2)
	v_add_f32_e32 v77, v83, v84
	s_waitcnt lgkmcnt(1)
	v_add_f32_e32 v74, v74, v75
	ds_bpermute_b32 v78, v168, v77
	ds_bpermute_b32 v75, v169, v74
	s_waitcnt lgkmcnt(2)
	v_add_f32_e32 v57, v57, v76
	ds_bpermute_b32 v76, v164, v57
	s_waitcnt lgkmcnt(2)
	v_add_f32_e32 v78, v77, v78
	s_waitcnt lgkmcnt(1)
	v_add_f32_e32 v80, v74, v75
	ds_bpermute_b32 v79, v167, v78
	ds_bpermute_b32 v81, v168, v80
	s_waitcnt lgkmcnt(2)
	v_add_f32_e32 v57, v57, v76
	ds_read_b128 v[74:77], v72 offset:12288
	s_waitcnt lgkmcnt(2)
	v_add_f32_e32 v82, v78, v79
	s_waitcnt lgkmcnt(1)
	v_add_f32_e32 v84, v80, v81
	ds_read_b128 v[78:81], v72 offset:12304
	s_waitcnt lgkmcnt(1)
	v_mul_f32_e32 v75, v65, v75
	v_fmac_f32_e32 v75, v64, v74
	v_mul_f32_e32 v74, v63, v77
	v_fmac_f32_e32 v74, v62, v76
	v_add_f32_e32 v74, v75, v74
	s_waitcnt lgkmcnt(0)
	v_mul_f32_e32 v79, v67, v79
	v_add_f32_e32 v85, 0, v74
	v_fmac_f32_e32 v79, v66, v78
	v_mul_f32_e32 v78, v33, v81
	ds_read_b128 v[74:77], v72 offset:14336
	v_fmac_f32_e32 v78, v32, v80
	v_add_f32_e32 v78, v79, v78
	v_add_f32_e32 v85, v85, v78
	ds_read_b128 v[78:81], v72 offset:14352
	s_waitcnt lgkmcnt(1)
	v_mul_f32_e32 v75, v31, v75
	v_fmac_f32_e32 v75, v30, v74
	v_mul_f32_e32 v74, v29, v77
	v_fmac_f32_e32 v74, v28, v76
	v_add_f32_e32 v74, v75, v74
	s_waitcnt lgkmcnt(0)
	v_mul_f32_e32 v79, v61, v79
	v_add_f32_e32 v85, v85, v74
	v_fmac_f32_e32 v79, v60, v78
	v_mul_f32_e32 v78, v59, v81
	ds_read_b128 v[74:77], v72 offset:16384
	v_fmac_f32_e32 v78, v58, v80
	v_add_f32_e32 v78, v79, v78
	v_add_f32_e32 v85, v85, v78
	ds_read_b128 v[78:81], v72 offset:16400
	s_waitcnt lgkmcnt(1)
	v_mul_f32_e32 v75, v65, v75
	v_fmac_f32_e32 v75, v64, v74
	v_mul_f32_e32 v74, v63, v77
	v_fmac_f32_e32 v74, v62, v76
	v_add_f32_e32 v74, v75, v74
	s_waitcnt lgkmcnt(0)
	v_mul_f32_e32 v79, v67, v79
	v_add_f32_e32 v87, 0, v74
	v_fmac_f32_e32 v79, v66, v78
	v_mul_f32_e32 v78, v33, v81
	ds_read_b128 v[74:77], v72 offset:18432
	v_fmac_f32_e32 v78, v32, v80
	v_add_f32_e32 v78, v79, v78
	v_add_f32_e32 v87, v87, v78
	ds_read_b128 v[78:81], v72 offset:18448
	s_waitcnt lgkmcnt(1)
	v_mul_f32_e32 v75, v31, v75
	v_fmac_f32_e32 v75, v30, v74
	v_mul_f32_e32 v74, v29, v77
	v_fmac_f32_e32 v74, v28, v76
	v_add_f32_e32 v74, v75, v74
	s_waitcnt lgkmcnt(0)
	v_mul_f32_e32 v75, v61, v79
	v_mul_f32_e32 v76, v59, v81
	v_fmac_f32_e32 v75, v60, v78
	v_fmac_f32_e32 v76, v58, v80
	v_add_f32_e32 v74, v87, v74
	v_add_f32_e32 v75, v75, v76
	v_add_f32_e32 v74, v74, v75
	ds_bpermute_b32 v86, v165, v85
	ds_bpermute_b32 v75, v165, v74
	ds_bpermute_b32 v76, v167, v84
	ds_bpermute_b32 v83, v166, v82
	s_waitcnt lgkmcnt(3)
	v_add_f32_e32 v77, v85, v86
	s_waitcnt lgkmcnt(2)
	v_add_f32_e32 v74, v74, v75
	ds_bpermute_b32 v78, v169, v77
	ds_bpermute_b32 v75, v169, v74
	s_waitcnt lgkmcnt(3)
	v_add_f32_e32 v76, v84, v76
	ds_bpermute_b32 v80, v166, v76
	s_waitcnt lgkmcnt(3)
	v_add_f32_e32 v79, v82, v83
	s_waitcnt lgkmcnt(2)
	v_add_f32_e32 v77, v77, v78
	s_waitcnt lgkmcnt(1)
	v_add_f32_e32 v74, v74, v75
	ds_bpermute_b32 v78, v168, v77
	ds_bpermute_b32 v75, v168, v74
	ds_bpermute_b32 v81, v164, v79
	s_waitcnt lgkmcnt(3)
	v_add_f32_e32 v76, v76, v80
	ds_bpermute_b32 v82, v164, v76
	s_waitcnt lgkmcnt(3)
	v_add_f32_e32 v77, v77, v78
	s_waitcnt lgkmcnt(2)
	v_add_f32_e32 v75, v74, v75
	ds_bpermute_b32 v78, v167, v77
	ds_bpermute_b32 v80, v167, v75
	s_waitcnt lgkmcnt(3)
	v_add_f32_e32 v74, v79, v81
	s_waitcnt lgkmcnt(1)
	v_add_f32_e32 v77, v77, v78
	s_waitcnt lgkmcnt(0)
	v_add_f32_e32 v79, v75, v80
	ds_bpermute_b32 v78, v166, v77
	ds_bpermute_b32 v84, v166, v79
	v_add_f32_e32 v75, v76, v82
	ds_read_b128 v[80:83], v72 offset:20480
	s_waitcnt lgkmcnt(2)
	v_add_f32_e32 v76, v77, v78
	s_waitcnt lgkmcnt(1)
	v_add_f32_e32 v78, v79, v84
	ds_read_b128 v[84:87], v72 offset:20496
	s_waitcnt lgkmcnt(1)
	v_mul_f32_e32 v81, v65, v81
	v_fmac_f32_e32 v81, v64, v80
	v_mul_f32_e32 v80, v63, v83
	v_fmac_f32_e32 v80, v62, v82
	v_add_f32_e32 v80, v81, v80
	s_waitcnt lgkmcnt(0)
	v_mul_f32_e32 v85, v67, v85
	v_add_f32_e32 v88, 0, v80
	v_fmac_f32_e32 v85, v66, v84
	v_mul_f32_e32 v84, v33, v87
	ds_read_b128 v[80:83], v72 offset:22528
	v_fmac_f32_e32 v84, v32, v86
	v_add_f32_e32 v84, v85, v84
	v_add_f32_e32 v88, v88, v84
	ds_read_b128 v[84:87], v72 offset:22544
	s_waitcnt lgkmcnt(1)
	v_mul_f32_e32 v81, v31, v81
	v_fmac_f32_e32 v81, v30, v80
	v_mul_f32_e32 v80, v29, v83
	v_fmac_f32_e32 v80, v28, v82
	v_add_f32_e32 v80, v81, v80
	s_waitcnt lgkmcnt(0)
	v_mul_f32_e32 v81, v61, v85
	v_fmac_f32_e32 v81, v60, v84
	ds_read_b128 v[82:85], v72 offset:24576
	v_mul_f32_e32 v87, v59, v87
	v_fmac_f32_e32 v87, v58, v86
	v_add_f32_e32 v80, v88, v80
	v_add_f32_e32 v81, v81, v87
	ds_read_b128 v[86:89], v72 offset:24592
	s_waitcnt lgkmcnt(1)
	v_pk_mul_f32 v[82:83], v[64:65], v[82:83]
	v_pk_mul_f32 v[84:85], v[62:63], v[84:85]
	v_add_f32_e32 v80, v80, v81
	v_pk_mov_b32 v[90:91], v[82:83], v[84:85] op_sel:[1,0]
	v_mov_b32_e32 v83, v85
	v_pk_add_f32 v[82:83], v[90:91], v[82:83]
	s_waitcnt lgkmcnt(0)
	v_pk_mul_f32 v[86:87], v[66:67], v[86:87]
	v_add_f32_e32 v82, v82, v83
	v_add_f32_e32 v94, 0, v82
	ds_read_b128 v[82:85], v72 offset:26624
	ds_read_b128 v[90:93], v72 offset:26640
	v_pk_mul_f32 v[88:89], v[32:33], v[88:89]
	ds_bpermute_b32 v81, v165, v80
	v_pk_mov_b32 v[96:97], v[86:87], v[88:89] op_sel:[1,0]
	v_mov_b32_e32 v87, v89
	v_pk_add_f32 v[86:87], v[96:97], v[86:87]
	s_waitcnt lgkmcnt(1)
; template <int LO, int HI> __global__ void __launch_bounds__(NWAVES * 64, 2) fox_fwd(Args args) {
;     ...
;                 fl[q] = wave_sum(a); }
;             float mine = fl[0];
; #pragma unroll
;             for (int q = 1; q < 8; ++q) mine = (lane == q) ? fl[q] : mine;
;             { const float z = mine + bfv; const float ls = fminf(z, 0.f) - log1pf(__expf(-fabsf(z)));
	v_mul_f32_e32 v88, v61, v91
	v_pk_add_f32 v[86:87], v[86:87], v[86:87] op_sel:[0,1] op_sel_hi:[1,0]
	v_mul_f32_e32 v95, v60, v90
	v_mov_b32_e32 v87, v88
	v_pk_add_f32 v[88:89], v[94:95], v[86:87]
	v_mul_f32_e32 v86, v31, v83
	v_pk_fma_f32 v[82:83], v[30:31], v[82:83], v[86:87] op_sel_hi:[1,1,0]
	v_mul_f32_e32 v86, v29, v85
	v_mul_f32_e32 v90, v58, v92
	v_mul_f32_e32 v91, v59, v93
	v_pk_fma_f32 v[84:85], v[28:29], v[84:85], v[86:87] op_sel_hi:[1,1,0]
	v_mov_b32_e32 v83, v90
	v_mov_b32_e32 v85, v91
	v_pk_add_f32 v[82:83], v[82:83], v[84:85]
	ds_read_b128 v[84:87], v72 offset:28672
	v_pk_add_f32 v[82:83], v[88:89], v[82:83]
	ds_read_b128 v[88:91], v72 offset:28688
	v_add_f32_e32 v82, v82, v83
	ds_bpermute_b32 v83, v165, v82
	s_waitcnt lgkmcnt(2)
	v_pk_mul_f32 v[64:65], v[64:65], v[84:85]
	v_pk_mul_f32 v[62:63], v[62:63], v[86:87]
	s_waitcnt lgkmcnt(1)
	v_pk_mul_f32 v[66:67], v[66:67], v[88:89]
	v_pk_mov_b32 v[84:85], v[64:65], v[62:63] op_sel:[1,0]
	v_mov_b32_e32 v65, v63
	v_pk_add_f32 v[62:63], v[84:85], v[64:65]
	v_pk_mul_f32 v[32:33], v[32:33], v[90:91]
	v_add_f32_e32 v62, v62, v63
	v_add_f32_e32 v92, 0, v62
	ds_read_b128 v[62:65], v72 offset:30720
	ds_read_b128 v[84:87], v72 offset:30736
	v_pk_mov_b32 v[88:89], v[66:67], v[32:33] op_sel:[1,0]
	v_mov_b32_e32 v67, v33
	v_pk_add_f32 v[32:33], v[88:89], v[66:67]
	ds_bpermute_b32 v77, v164, v76
	s_waitcnt lgkmcnt(1)
	v_mul_f32_e32 v93, v60, v84
	v_mul_f32_e32 v60, v61, v85
	v_mul_f32_e32 v61, v58, v86
	v_mul_f32_e32 v59, v59, v87
	v_mul_f32_e32 v58, v31, v63
	v_pk_fma_f32 v[30:31], v[30:31], v[62:63], v[58:59] op_sel_hi:[1,1,0]
	v_mul_f32_e32 v58, v29, v65
	v_pk_add_f32 v[32:33], v[32:33], v[32:33] op_sel:[0,1] op_sel_hi:[1,0]
	v_pk_fma_f32 v[28:29], v[28:29], v[64:65], v[58:59] op_sel_hi:[1,1,0]
	v_mov_b32_e32 v33, v60
	v_mov_b32_e32 v31, v61
	v_mov_b32_e32 v29, v59
	v_pk_add_f32 v[32:33], v[92:93], v[32:33]
	v_pk_add_f32 v[28:29], v[30:31], v[28:29]
	v_add_f32_e32 v30, v80, v81
	v_pk_add_f32 v[28:29], v[32:33], v[28:29]
	ds_bpermute_b32 v31, v169, v30
	v_add_f32_e32 v28, v28, v29
	ds_bpermute_b32 v29, v165, v28
	v_add_f32_e32 v32, v82, v83
	ds_bpermute_b32 v33, v169, v32
	s_waitcnt lgkmcnt(2)
	v_add_f32_e32 v30, v30, v31
	ds_bpermute_b32 v31, v168, v30
	s_waitcnt lgkmcnt(2)
	v_add_f32_e32 v28, v28, v29
	ds_bpermute_b32 v29, v169, v28
	s_waitcnt lgkmcnt(2)
	v_add_f32_e32 v32, v32, v33
	ds_bpermute_b32 v33, v168, v32
	s_waitcnt lgkmcnt(2)
	v_add_f32_e32 v30, v30, v31
	ds_bpermute_b32 v31, v167, v30
	s_waitcnt lgkmcnt(2)
	v_add_f32_e32 v28, v28, v29
	ds_bpermute_b32 v29, v168, v28
	s_waitcnt lgkmcnt(2)
	v_add_f32_e32 v32, v32, v33
	ds_bpermute_b32 v33, v167, v32
	s_waitcnt lgkmcnt(2)
	v_add_f32_e32 v30, v30, v31
	ds_bpermute_b32 v31, v166, v30
	s_waitcnt lgkmcnt(2)
	v_add_f32_e32 v28, v28, v29
	ds_bpermute_b32 v29, v167, v28
	s_waitcnt lgkmcnt(2)
	v_add_f32_e32 v32, v32, v33
	ds_bpermute_b32 v33, v166, v32
	ds_bpermute_b32 v79, v164, v78
	s_waitcnt lgkmcnt(3)
	v_add_f32_e32 v30, v30, v31
	s_waitcnt lgkmcnt(2)
	v_add_f32_e32 v28, v28, v29
	ds_bpermute_b32 v29, v166, v28
	ds_bpermute_b32 v31, v164, v30
	s_waitcnt lgkmcnt(3)
	v_add_f32_e32 v32, v32, v33
	ds_bpermute_b32 v33, v164, v32
	v_add_f32_e32 v58, v76, v77
	s_waitcnt lgkmcnt(2)
	v_add_f32_e32 v28, v28, v29
	ds_bpermute_b32 v29, v164, v28
	v_add_f32_e32 v59, v78, v79
	s_waitcnt lgkmcnt(2)
	v_add_f32_e32 v30, v30, v31
	s_waitcnt lgkmcnt(1)
	v_add_f32_e32 v31, v32, v33
	global_store_dwordx4 v[24:25], v[18:21], off offset:1024
	s_waitcnt lgkmcnt(0)
	v_add_f32_e32 v28, v28, v29
	v_cndmask_b32_e64 v29, v57, v74, s[4:5]
	v_cndmask_b32_e64 v29, v29, v75, s[6:7]
	v_cndmask_b32_e64 v29, v29, v58, s[8:9]
	v_cndmask_b32_e64 v29, v29, v59, s[10:11]
	v_cndmask_b32_e64 v29, v29, v30, s[12:13]
	v_cndmask_b32_e64 v29, v29, v31, s[14:15]
	v_cndmask_b32_e64 v28, v29, v28, s[16:17]
	v_add_f32_e32 v29, v71, v28
	v_mul_f32_e64 v28, |v29|, s29
	v_exp_f32_e32 v78, v28
	v_ldexp_f32 v28, v23, v27
	v_min_f32_e32 v23, 0, v29
	v_add_f32_e32 v20, 1.0, v78
	v_add_f32_e32 v18, -1.0, v20
	v_sub_f32_e32 v19, v18, v20
	v_add_f32_e32 v19, 1.0, v19
	v_sub_f32_e32 v18, v78, v18
	v_add_f32_e32 v21, v18, v19
	v_frexp_mant_f32_e32 v24, v20
	v_cvt_f64_f32_e32 v[18:19], v20
	v_frexp_exp_i32_f64_e32 v18, v[18:19]
	v_cmp_gt_f32_e32 vcc, s37, v24
	s_nop 1
	v_subbrev_co_u32_e32 v57, vcc, 0, v18, vcc
	v_sub_u32_e32 v18, 0, v57
	v_ldexp_f32 v27, v20, v18
	v_ldexp_f32 v29, v21, v18
	v_pk_add_f32 v[18:19], v[26:27], 1.0 op_sel_hi:[1,0]
	v_pk_add_f32 v[32:33], v[26:27], -1.0 op_sel_hi:[1,0]
	v_pk_add_f32 v[20:21], v[18:19], -1.0 op_sel_hi:[1,0]
	v_pk_add_f32 v[58:59], v[32:33], 1.0 op_sel_hi:[1,0]
	v_pk_add_f32 v[20:21], v[26:27], v[20:21] neg_lo:[0,1] neg_hi:[0,1]
	v_pk_add_f32 v[26:27], v[26:27], v[58:59] neg_lo:[0,1] neg_hi:[0,1]
	v_pk_add_f32 v[20:21], v[28:29], v[20:21]
	v_pk_add_f32 v[26:27], v[28:29], v[26:27]
	v_pk_add_f32 v[24:25], v[18:19], v[20:21]
	v_pk_add_f32 v[28:29], v[32:33], v[26:27]
	v_rcp_f32_e32 v30, v24
	v_rcp_f32_e32 v31, v25
	v_pk_add_f32 v[18:19], v[24:25], v[18:19] neg_lo:[0,1] neg_hi:[0,1]
	v_pk_add_f32 v[32:33], v[28:29], v[32:33] neg_lo:[0,1] neg_hi:[0,1]
	v_pk_add_f32 v[18:19], v[20:21], v[18:19] neg_lo:[0,1] neg_hi:[0,1]
	v_pk_mul_f32 v[20:21], v[28:29], v[30:31]
	v_pk_add_f32 v[26:27], v[26:27], v[32:33] neg_lo:[0,1] neg_hi:[0,1]
	v_pk_mul_f32 v[32:33], v[24:25], v[20:21]
	v_cmp_neq_f32_e32 vcc, s46, v55
	v_pk_fma_f32 v[58:59], v[20:21], v[24:25], v[32:33] neg_lo:[0,0,1] neg_hi:[0,0,1]
	s_nop 0
	v_pk_fma_f32 v[58:59], v[20:21], v[18:19], v[58:59]
	s_nop 0
	v_pk_add_f32 v[60:61], v[32:33], v[58:59]
	s_nop 0
	v_pk_add_f32 v[62:63], v[28:29], v[60:61] neg_lo:[0,1] neg_hi:[0,1]
; template <int LO, int HI> __global__ void __launch_bounds__(NWAVES * 64, 2) fox_fwd(Args args) {
;     ...
;             { const float z = mine + bfv; const float ls = fminf(z, 0.f) - log1pf(__expf(-fabsf(z)));
; #pragma unroll
;               for (int k = 0; k < 4; ++k)
; #pragma unroll
;                   for (int e = 0; e < 4; ++e) lsq[k][e] = (r == 4 * k + e) ? ls : lsq[k][e]; }
	v_pk_add_f32 v[32:33], v[60:61], v[32:33] neg_lo:[0,1] neg_hi:[0,1]
	v_pk_add_f32 v[28:29], v[28:29], v[62:63] neg_lo:[0,1] neg_hi:[0,1]
	s_nop 0
	v_pk_add_f32 v[28:29], v[28:29], v[60:61] neg_lo:[0,1] neg_hi:[0,1]
	s_nop 0
	v_pk_add_f32 v[26:27], v[26:27], v[28:29]
	v_pk_add_f32 v[28:29], v[32:33], v[58:59] neg_lo:[0,1] neg_hi:[0,1]
	s_nop 0
	v_pk_add_f32 v[26:27], v[28:29], v[26:27]
	s_nop 0
	v_pk_add_f32 v[28:29], v[62:63], v[26:27]
	s_nop 0
	v_pk_mul_f32 v[32:33], v[30:31], v[28:29]
	s_nop 0
	v_pk_mul_f32 v[58:59], v[24:25], v[32:33]
	s_nop 0
	v_pk_fma_f32 v[24:25], v[32:33], v[24:25], v[58:59] neg_lo:[0,0,1] neg_hi:[0,0,1]
	s_nop 0
	v_pk_fma_f32 v[18:19], v[32:33], v[18:19], v[24:25]
	v_pk_add_f32 v[24:25], v[62:63], v[28:29] neg_lo:[0,1] neg_hi:[0,1]
	s_nop 0
	v_pk_add_f32 v[24:25], v[26:27], v[24:25]
	v_pk_add_f32 v[26:27], v[58:59], v[18:19]
	s_nop 0
	v_pk_add_f32 v[60:61], v[28:29], v[26:27] neg_lo:[0,1] neg_hi:[0,1]
	v_pk_add_f32 v[58:59], v[26:27], v[58:59] neg_lo:[0,1] neg_hi:[0,1]
	v_pk_add_f32 v[28:29], v[28:29], v[60:61] neg_lo:[0,1] neg_hi:[0,1]
	v_pk_add_f32 v[18:19], v[58:59], v[18:19] neg_lo:[0,1] neg_hi:[0,1]
	v_pk_add_f32 v[26:27], v[28:29], v[26:27] neg_lo:[0,1] neg_hi:[0,1]
	s_nop 0
	v_pk_add_f32 v[24:25], v[24:25], v[26:27]
	s_nop 0
	v_pk_add_f32 v[18:19], v[18:19], v[24:25]
	v_pk_add_f32 v[24:25], v[20:21], v[32:33]
	v_pk_add_f32 v[18:19], v[60:61], v[18:19]
	v_pk_add_f32 v[20:21], v[24:25], v[20:21] neg_lo:[0,1] neg_hi:[0,1]
	v_pk_mul_f32 v[18:19], v[30:31], v[18:19]
	v_pk_add_f32 v[20:21], v[32:33], v[20:21] neg_lo:[0,1] neg_hi:[0,1]
	v_cvt_f32_i32_e32 v32, v56
	v_pk_add_f32 v[18:19], v[20:21], v[18:19]
	v_cvt_f32_i32_e32 v33, v57
	v_pk_add_f32 v[26:27], v[24:25], v[18:19]
	s_nop 0
	v_pk_add_f32 v[20:21], v[26:27], v[24:25] neg_lo:[0,1] neg_hi:[0,1]
	v_pk_mul_f32 v[28:29], v[26:27], v[26:27]
	v_pk_add_f32 v[18:19], v[18:19], v[20:21] neg_lo:[0,1] neg_hi:[0,1]
	v_mov_b32_e32 v20, 0x3ecc95a3
	v_pk_fma_f32 v[30:31], v[28:29], s[20:21], v[20:21] op_sel_hi:[1,0,0]
	s_mov_b32 s20, 0x3f2aaada
	v_ldexp_f32 v24, v26, 1
	v_pk_fma_f32 v[30:31], v[28:29], v[30:31], s[20:21] op_sel_hi:[1,1,0]
	v_ldexp_f32 v25, v27, 1
	v_pk_mul_f32 v[26:27], v[26:27], v[28:29]
	v_pk_mul_f32 v[28:29], v[32:33], s[36:37] op_sel_hi:[1,0]
	v_pk_mul_f32 v[26:27], v[26:27], v[30:31]
	v_pk_fma_f32 v[58:59], v[32:33], s[36:37], v[28:29] op_sel_hi:[1,0,1] neg_lo:[0,0,1] neg_hi:[0,0,1]
	v_pk_add_f32 v[30:31], v[24:25], v[26:27]
	s_mov_b32 s20, 0xb102e308
	v_pk_add_f32 v[24:25], v[30:31], v[24:25] neg_lo:[0,1] neg_hi:[0,1]
	v_ldexp_f32 v57, v19, 1
	v_pk_fma_f32 v[32:33], v[32:33], s[20:21], v[58:59] op_sel_hi:[1,0,1]
	v_pk_add_f32 v[24:25], v[26:27], v[24:25] neg_lo:[0,1] neg_hi:[0,1]
	v_ldexp_f32 v18, v18, 1
	v_mov_b32_e32 v26, v28
	v_mov_b32_e32 v27, v25
	v_mov_b32_e32 v56, v32
	v_mov_b32_e32 v19, v57
	v_pk_add_f32 v[26:27], v[26:27], v[56:57]
	v_pk_add_f32 v[56:57], v[18:19], v[24:25]
	v_mov_b32_e32 v25, v31
	v_mov_b32_e32 v19, v57
	v_pk_add_f32 v[58:59], v[28:29], v[32:33]
	v_pk_add_f32 v[18:19], v[18:19], v[24:25]
	v_pk_add_f32 v[24:25], v[30:31], v[56:57]
	v_mov_b32_e32 v74, v30
	v_pk_add_f32 v[60:61], v[58:59], v[24:25]
	v_mov_b32_e32 v66, v24
	v_mov_b32_e32 v67, v61
	v_mov_b32_e32 v75, v59
	v_pk_add_f32 v[66:67], v[66:67], v[74:75] neg_lo:[0,1] neg_hi:[0,1]
	v_mov_b32_e32 v62, v60
	v_mov_b32_e32 v63, v59
	v_mov_b32_e32 v64, v58
	v_mov_b32_e32 v65, v29
	v_mov_b32_e32 v74, v58
	v_mov_b32_e32 v75, v61
	v_mov_b32_e32 v29, v67
	v_pk_add_f32 v[62:63], v[62:63], v[64:65] neg_lo:[0,1] neg_hi:[0,1]
	v_mov_b32_e32 v64, v24
	v_mov_b32_e32 v65, v33
	v_pk_add_f32 v[28:29], v[74:75], v[28:29] neg_lo:[0,1] neg_hi:[0,1]
	v_pk_add_f32 v[64:65], v[64:65], v[62:63] neg_lo:[0,1] neg_hi:[0,1]
	v_mov_b32_e32 v74, v28
	v_mov_b32_e32 v75, v63
	v_mov_b32_e32 v76, v60
	v_mov_b32_e32 v77, v25
	v_mov_b32_e32 v63, v31
	v_pk_add_f32 v[74:75], v[32:33], v[74:75] neg_lo:[0,1] neg_hi:[0,1]
	v_pk_add_f32 v[62:63], v[76:77], v[62:63] neg_lo:[0,1] neg_hi:[0,1]
	v_mov_b32_e32 v33, v59
	v_pk_add_f32 v[26:27], v[26:27], v[62:63] neg_lo:[0,1] neg_hi:[0,1]
	v_pk_add_f32 v[28:29], v[32:33], v[28:29] neg_lo:[0,1] neg_hi:[0,1]
	v_pk_add_f32 v[18:19], v[18:19], v[66:67] neg_lo:[0,1] neg_hi:[0,1]
	v_pk_add_f32 v[24:25], v[24:25], v[30:31] neg_lo:[0,1] neg_hi:[0,1]
	v_pk_add_f32 v[30:31], v[18:19], v[28:29]
	v_mov_b32_e32 v29, v65
	v_mov_b32_e32 v19, v27
	v_pk_add_f32 v[32:33], v[64:65], v[26:27]
	v_pk_add_f32 v[18:19], v[28:29], v[18:19]
	v_mov_b32_e32 v26, v30
	v_pk_add_f32 v[18:19], v[18:19], v[74:75] neg_lo:[0,1] neg_hi:[0,1]
	v_mov_b32_e32 v27, v33
	v_pk_add_f32 v[24:25], v[56:57], v[24:25] neg_lo:[0,1] neg_hi:[0,1]
	v_pk_add_f32 v[26:27], v[26:27], v[18:19] neg_lo:[0,1] neg_hi:[0,1]
	v_pk_add_f32 v[18:19], v[24:25], v[18:19] neg_lo:[0,1] neg_hi:[0,1]
	v_pk_add_f32 v[26:27], v[28:29], v[26:27] neg_lo:[0,1] neg_hi:[0,1]
	v_pk_add_f32 v[24:25], v[32:33], v[30:31]
	v_pk_add_f32 v[18:19], v[18:19], v[26:27]
	v_pk_add_f32 v[26:27], v[60:61], v[24:25]
	v_mov_b32_e32 v64, 0x7f800000
	v_pk_add_f32 v[28:29], v[26:27], v[60:61] neg_lo:[0,1] neg_hi:[0,1]
	v_mov_b32_e32 v65, 0x7fc00000
	v_pk_add_f32 v[24:25], v[24:25], v[28:29] neg_lo:[0,1] neg_hi:[0,1]
	v_mov_b32_e32 v66, 0xff800000
	v_pk_add_f32 v[18:19], v[18:19], v[24:25]
	s_add_u32 s20, s26, s34
	v_pk_add_f32 v[18:19], v[26:27], v[18:19]
	s_addc_u32 s21, s27, s35
	v_cndmask_b32_e32 v18, v64, v18, vcc
	v_cmp_neq_f32_e32 vcc, s46, v78
	s_mov_b64 s[34:35], 0x2000
	v_mov_b32_e32 v58, 0x3f317218
	v_cndmask_b32_e32 v19, v64, v19, vcc
	v_cmp_ngt_f32_e32 vcc, -1.0, v78
	v_mov_b32_e32 v21, v37
	v_mov_b32_e32 v30, v37
	v_cndmask_b32_e32 v19, v65, v19, vcc
; #define GAS __attribute__((address_space(1)))
; __device__ __forceinline__ unsigned pk2(float lo, float hi) { return pg8::cvt_pk_bf16(lo, hi); }
; template <int LO, int HI> __global__ void __launch_bounds__(NWAVES * 64, 2) fox_fwd(Args args) {
;     ...
;         for (int r = 0; r < 16; ++r) { const int m = m0 + r;
;             const GAS float* xr = (const GAS float*)(x + (size_t)m * D);
;             f32x4 v[4]; float s2 = 0.f;
; #pragma unroll
;             for (int j = 0; j < 4; ++j) { v[j] = *(const GAS f32x4*)(xr + P1COL(j)); s2 += (v[j][0] * v[j][0] + v[j][1] * v[j][1]) + (v[j][2] * v[j][2] + v[j][3] * v[j][3]); }
;             const float rstd = 1.0f / sqrtf(wave_sum(s2) * (1.0f / D) + EPS);
; #pragma unroll
;             for (int j = 0; j < 4; ++j) v[j] = v[j] * rstd * gm[j] + sh[j];
; #pragma unroll
;             for (int j = 0; j < 2; ++j) { v4u o; o.x = pk2(v[2 * j][0], v[2 * j][1]); o.y = pk2(v[2 * j][2], v[2 * j][3]); o.z = pk2(v[2 * j + 1][0], v[2 * j + 1][1]); o.w = pk2(v[2 * j + 1][2], v[2 * j + 1][3]);
;                 *(GAS v4u*)(HB + (size_t)m * D + 8 * lane + 512 * j) = o; }
	v_cmp_ngt_f32_e32 vcc, -1.0, v55
	v_mov_b32_e32 v31, v37
	v_mov_b32_e32 v32, v37
	v_cndmask_b32_e32 v18, v65, v18, vcc
	v_cmp_neq_f32_e32 vcc, -1.0, v55
	v_mov_b32_e32 v33, v37
	v_mov_b32_e32 v26, v37
	v_cndmask_b32_e32 v18, v66, v18, vcc
	v_cmp_neq_f32_e32 vcc, -1.0, v78
	v_mov_b32_e32 v27, v37
	v_mov_b32_e32 v28, v37
	v_cndmask_b32_e32 v19, v66, v19, vcc
	v_cmp_lt_f32_e64 vcc, |v78|, s47
	v_mov_b32_e32 v29, v37
	v_mov_b32_e32 v24, v37
	v_cndmask_b32_e32 v19, v19, v78, vcc
	v_cmp_lt_f32_e64 vcc, |v55|, s47
	v_mov_b32_e32 v25, v37
	s_nop 0
	v_cndmask_b32_e32 v18, v18, v55, vcc
	v_pk_add_f32 v[18:19], v[22:23], v[18:19] neg_lo:[0,1] neg_hi:[0,1]
	v_mov_b32_e32 v55, v37
	v_lshl_add_u64 v[22:23], s[20:21], 0, v[36:37]
	s_mov_b64 s[20:21], 0x2001400
	v_lshl_add_u64 v[54:55], s[30:31], 0, v[54:55]
	v_lshl_add_u64 v[56:57], v[22:23], 0, s[20:21]
	s_mov_b64 s[30:31], 0
	v_mov_b32_e32 v22, v37
	v_mov_b32_e32 v23, v37
	s_mov_b64 s[50:51], 0x2000
	v_mov_b32_e32 v244, 0
	v_mov_b32_e32 v245, 0
	v_lshl_add_u64 v[242:243], v[54:55], 0, v[244:245]
	v_lshl_add_u64 v[246:247], v[242:243], 0, s[34:35]
	v_lshl_add_u64 v[248:249], v[242:243], 0, s[38:39]
	v_lshl_add_u64 v[250:251], v[242:243], 0, s[50:51]
	global_load_dwordx4 v[226:229], v[250:251], off
	global_load_dwordx4 v[230:233], v[246:247], off offset:16
	global_load_dwordx4 v[234:237], v[248:249], off offset:16
	global_load_dwordx4 v[238:241], v[250:251], off offset:2048
.LBB0_131:
	s_waitcnt vmcnt(0)
	v_mov_b32_e32 v60, v226
	v_mov_b32_e32 v61, v227
	v_mov_b32_e32 v62, v228
	v_mov_b32_e32 v63, v229
	v_mov_b32_e32 v74, v230
	v_mov_b32_e32 v75, v231
	v_mov_b32_e32 v76, v232
	v_mov_b32_e32 v77, v233
	v_mov_b32_e32 v78, v234
	v_mov_b32_e32 v79, v235
	v_mov_b32_e32 v80, v236
	v_mov_b32_e32 v81, v237
	v_mov_b32_e32 v82, v238
	v_mov_b32_e32 v83, v239
	v_mov_b32_e32 v84, v240
	v_mov_b32_e32 v85, v241
	s_cmp_eq_u32 s30, 0
	v_pk_mul_f32 v[86:87], v[62:63], v[62:63]
	v_pk_mul_f32 v[88:89], v[60:61], v[60:61]
	v_pk_mul_f32 v[90:91], v[76:77], v[76:77]
	v_pk_mul_f32 v[92:93], v[74:75], v[74:75]
	v_pk_mov_b32 v[96:97], v[88:89], v[86:87] op_sel:[1,0]
	v_mov_b32_e32 v89, v87
	v_pk_mov_b32 v[86:87], v[92:93], v[90:91] op_sel:[1,0]
	v_mov_b32_e32 v93, v91
	v_mul_f32_e32 v36, v83, v83
	v_mul_f32_e32 v94, v85, v85
	v_pk_add_f32 v[88:89], v[96:97], v[88:89]
	v_pk_add_f32 v[86:87], v[86:87], v[92:93]
	v_mul_f32_e32 v59, v78, v78
	v_mul_f32_e32 v67, v79, v79
	v_mul_f32_e32 v98, v80, v80
	v_mul_f32_e32 v99, v81, v81
	v_pk_fma_f32 v[90:91], v[82:83], v[82:83], v[36:37] op_sel_hi:[1,1,0]
	v_pk_fma_f32 v[94:95], v[84:85], v[84:85], v[94:95] op_sel_hi:[1,1,0]
	v_pk_add_f32 v[88:89], v[88:89], v[88:89] op_sel:[0,1] op_sel_hi:[1,0]
	v_pk_add_f32 v[86:87], v[86:87], v[86:87] op_sel:[0,1] op_sel_hi:[1,0]
	v_mov_b32_e32 v91, v98
	v_mov_b32_e32 v95, v99
	v_mov_b32_e32 v89, v59
	v_mov_b32_e32 v87, v67
	v_pk_add_f32 v[90:91], v[90:91], v[94:95]
	v_pk_add_f32 v[86:87], v[88:89], v[86:87]
	s_nop 0
	v_pk_add_f32 v[86:87], v[86:87], v[90:91]
	s_nop 0
	v_add_f32_e32 v36, v86, v87
	ds_bpermute_b32 v59, v165, v36
	s_waitcnt lgkmcnt(0)
	v_add_f32_e32 v36, v36, v59
	ds_bpermute_b32 v59, v169, v36
	s_waitcnt lgkmcnt(0)
	v_add_f32_e32 v36, v36, v59
	ds_bpermute_b32 v59, v168, v36
	s_waitcnt lgkmcnt(0)
	v_add_f32_e32 v36, v36, v59
	ds_bpermute_b32 v59, v167, v36
	s_waitcnt lgkmcnt(0)
	v_add_f32_e32 v36, v36, v59
	ds_bpermute_b32 v59, v166, v36
	s_waitcnt lgkmcnt(0)
	v_add_f32_e32 v36, v36, v59
	ds_bpermute_b32 v59, v164, v36
	s_waitcnt lgkmcnt(0)
	v_add_f32_e32 v36, v36, v59
	v_fmamk_f32 v36, v36, 0x3a800000, v69
	v_mul_f32_e32 v59, 0x4f800000, v36
	v_cmp_gt_f32_e32 vcc, s45, v36
	s_nop 1
	v_cndmask_b32_e32 v36, v36, v59, vcc
	v_sqrt_f32_e32 v59, v36
	s_nop 0
	v_add_u32_e32 v67, -1, v59
	v_add_u32_e32 v86, 1, v59
	v_fma_f32 v87, -v67, v59, v36
	v_fma_f32 v88, -v86, v59, v36
	v_cmp_ge_f32_e64 s[20:21], 0, v87
	s_nop 1
	v_cndmask_b32_e64 v59, v59, v67, s[20:21]
	v_cmp_lt_f32_e64 s[20:21], 0, v88
	s_nop 1
	v_cndmask_b32_e64 v59, v59, v86, s[20:21]
	v_mul_f32_e32 v67, 0x37800000, v59
	v_cndmask_b32_e32 v59, v59, v67, vcc
	v_cmp_class_f32_e32 vcc, v36, v70
	s_nop 1
	v_cndmask_b32_e32 v36, v59, v36, vcc
	v_div_scale_f32 v59, s[20:21], v36, v36, 1.0
	v_rcp_f32_e32 v86, v59
	v_div_scale_f32 v67, vcc, 1.0, v36, 1.0
	v_fma_f32 v87, -v59, v86, 1.0
	v_fmac_f32_e32 v86, v87, v86
	v_mul_f32_e32 v87, v67, v86
	v_fma_f32 v88, -v59, v87, v67
	v_fmac_f32_e32 v87, v88, v86
	v_fma_f32 v59, -v59, v87, v67
	v_div_fmas_f32 v59, v59, v86, v87
	v_div_fixup_f32 v36, v59, v36, 1.0
	v_pk_mul_f32 v[60:61], v[36:37], v[60:61] op_sel_hi:[0,1]
	v_pk_mul_f32 v[62:63], v[36:37], v[62:63] op_sel_hi:[0,1]
	v_pk_mul_f32 v[74:75], v[36:37], v[74:75] op_sel_hi:[0,1]
	v_pk_mul_f32 v[76:77], v[36:37], v[76:77] op_sel_hi:[0,1]
	v_pk_mul_f32 v[82:83], v[36:37], v[82:83] op_sel_hi:[0,1]
	v_pk_mul_f32 v[84:85], v[36:37], v[84:85] op_sel_hi:[0,1]
	v_pk_mul_f32 v[78:79], v[36:37], v[78:79] op_sel_hi:[0,1]
	v_pk_mul_f32 v[80:81], v[36:37], v[80:81] op_sel_hi:[0,1]
	v_pk_fma_f32 v[162:163], v[38:39], v[62:63], v[8:9]
	v_pk_fma_f32 v[214:215], v[40:41], v[60:61], v[6:7]
	v_pk_fma_f32 v[216:217], v[42:43], v[76:77], v[4:5]
	v_pk_fma_f32 v[218:219], v[44:45], v[74:75], v[2:3]
	v_cvt_pk_bf16_f32 v74, v214, v215
	v_cvt_pk_bf16_f32 v75, v162, v163
	v_pk_fma_f32 v[60:61], v[46:47], v[84:85], v[16:17]
	v_cvt_pk_bf16_f32 v76, v218, v219
	v_cvt_pk_bf16_f32 v77, v216, v217
	v_pk_fma_f32 v[62:63], v[48:49], v[82:83], v[14:15]
	v_pk_fma_f32 v[220:221], v[50:51], v[80:81], v[12:13]
	v_pk_fma_f32 v[222:223], v[52:53], v[78:79], v[10:11]
	global_store_dwordx4 v[56:57], v[74:77], off offset:-1024
	s_nop 1
; #define GAS __attribute__((address_space(1)))
; #define LAS __attribute__((address_space(3)))
; __device__ __forceinline__ unsigned pk2(float lo, float hi) { return pg8::cvt_pk_bf16(lo, hi); }
; template <int LO, int HI> __global__ void __launch_bounds__(NWAVES * 64, 2) fox_fwd(Args args) {
;     ...
;         for (int r = 0; r < 16; ++r) { const int m = m0 + r;
;             const GAS float* xr = (const GAS float*)(x + (size_t)m * D);
;             f32x4 v[4]; float s2 = 0.f;
; #pragma unroll
;             for (int j = 0; j < 4; ++j) { v[j] = *(const GAS f32x4*)(xr + P1COL(j)); s2 += (v[j][0] * v[j][0] + v[j][1] * v[j][1]) + (v[j][2] * v[j][2] + v[j][3] * v[j][3]); }
;             const float rstd = 1.0f / sqrtf(wave_sum(s2) * (1.0f / D) + EPS);
; #pragma unroll
;             for (int j = 0; j < 4; ++j) v[j] = v[j] * rstd * gm[j] + sh[j];
; #pragma unroll
;             for (int j = 0; j < 2; ++j) { v4u o; o.x = pk2(v[2 * j][0], v[2 * j][1]); o.y = pk2(v[2 * j][2], v[2 * j][3]); o.z = pk2(v[2 * j + 1][0], v[2 * j + 1][1]); o.w = pk2(v[2 * j + 1][2], v[2 * j + 1][3]);
;                 *(GAS v4u*)(HB + (size_t)m * D + 8 * lane + 512 * j) = o; }
;             float fl[8];
; #pragma unroll
;             for (int q = 0; q < 8; ++q) { float a = 0.f;
; #pragma unroll
;                 for (int j = 0; j < 4; ++j) { const f32x4 w = *(const LAS f32x4*)(wf + q * 1024 + P1COL(j)); a += (v[j][0] * w[0] + v[j][1] * w[1]) + (v[j][2] * w[2] + v[j][3] * w[3]); }
;                 fl[q] = wave_sum(a); }
	v_cvt_pk_bf16_f32 v74, v62, v63
	v_cvt_pk_bf16_f32 v75, v60, v61
	v_cvt_pk_bf16_f32 v76, v222, v223
	v_cvt_pk_bf16_f32 v77, v220, v221
	ds_read_b128 v[78:81], v72
	ds_read_b128 v[82:85], v72 offset:16
	ds_read_b128 v[86:89], v72 offset:2048
	ds_read_b128 v[90:93], v72 offset:2064
	ds_read_b128 v[94:97], v72 offset:4096
	ds_read_b128 v[98:101], v72 offset:4112
	ds_read_b128 v[102:105], v72 offset:6144
	ds_read_b128 v[106:109], v72 offset:6160
	ds_read_b128 v[110:113], v72 offset:8192
	ds_read_b128 v[114:117], v72 offset:8208
	ds_read_b128 v[118:121], v72 offset:10240
	ds_read_b128 v[122:125], v72 offset:10256
	ds_read_b128 v[126:129], v72 offset:12288
	ds_read_b128 v[130:133], v72 offset:12304
	ds_read_b128 v[134:137], v72 offset:14336
	ds_read_b128 v[138:141], v72 offset:14352
	ds_read_b128 v[142:145], v72 offset:16384
	ds_read_b128 v[146:149], v72 offset:16400
	ds_read_b128 v[150:153], v72 offset:18432
	ds_read_b128 v[154:157], v72 offset:18448
	ds_read_b128 v[158:161], v72 offset:20480
	ds_read_b128 v[170:173], v72 offset:20496
	ds_read_b128 v[174:177], v72 offset:22528
	ds_read_b128 v[178:181], v72 offset:22544
	ds_read_b128 v[182:185], v72 offset:24576
	ds_read_b128 v[186:189], v72 offset:24592
	ds_read_b128 v[190:193], v72 offset:26624
	ds_read_b128 v[194:197], v72 offset:26640
	ds_read_b128 v[198:201], v72 offset:28672
	ds_read_b128 v[202:205], v72 offset:28688
	ds_read_b128 v[206:209], v72 offset:30720
	ds_read_b128 v[210:213], v72 offset:30736
	s_waitcnt lgkmcnt(14)
	v_mul_f32_e32 v59, v215, v79
	v_mul_f32_e32 v67, v163, v81
	v_mul_f32_e32 v89, v61, v89
	v_mul_f32_e32 v91, v223, v91
	v_mul_f32_e32 v95, v215, v95
	v_mul_f32_e32 v97, v163, v97
	global_store_dwordx4 v[56:57], v[74:77], off
	v_mov_b32_e32 v244, s30
	v_add_u32_e32 v244, 0x1000, v244
	v_min_u32_e32 v244, 0xd000, v244
	v_mov_b32_e32 v245, 0
	v_lshl_add_u64 v[242:243], v[54:55], 0, v[244:245]
	v_lshl_add_u64 v[246:247], v[242:243], 0, s[34:35]
	v_lshl_add_u64 v[248:249], v[242:243], 0, s[38:39]
	v_lshl_add_u64 v[250:251], v[242:243], 0, s[50:51]
	global_load_dwordx4 v[226:229], v[250:251], off
	global_load_dwordx4 v[230:233], v[246:247], off offset:16
	global_load_dwordx4 v[234:237], v[248:249], off offset:16
	global_load_dwordx4 v[238:241], v[250:251], off offset:2048
	v_mul_f32_e32 v224, v219, v83
	v_mul_f32_e32 v225, v217, v85
	v_mul_f32_e32 v87, v63, v87
	v_mul_f32_e32 v93, v221, v93
	v_mul_f32_e32 v99, v219, v99
	v_mul_f32_e32 v101, v217, v101
	v_mul_f32_e32 v103, v63, v103
	v_mul_f32_e32 v111, v215, v111
	v_mul_f32_e32 v113, v163, v113
	v_mul_f32_e32 v119, v63, v119
	v_mul_f32_e32 v127, v215, v127
	v_mul_f32_e32 v129, v163, v129
	v_mul_f32_e32 v135, v63, v135
	v_mul_f32_e32 v143, v215, v143
	v_mul_f32_e32 v145, v163, v145
	s_waitcnt lgkmcnt(13)
	v_mul_f32_e32 v151, v63, v151
	v_fmac_f32_e32 v59, v214, v78
	v_fmac_f32_e32 v67, v162, v80
	s_waitcnt lgkmcnt(11)
	v_mul_f32_e32 v159, v215, v159
	v_mul_f32_e32 v161, v163, v161
	s_waitcnt lgkmcnt(9)
	v_mul_f32_e32 v175, v63, v175
	v_fmac_f32_e32 v89, v60, v88
	s_waitcnt lgkmcnt(8)
	v_mul_f32_e32 v88, v223, v179
	s_waitcnt lgkmcnt(7)
	v_mul_f32_e32 v179, v215, v183
	v_fmac_f32_e32 v91, v222, v90
	v_mul_f32_e32 v90, v163, v185
	s_waitcnt lgkmcnt(5)
	v_mul_f32_e32 v183, v63, v191
	v_fmac_f32_e32 v95, v214, v94
	v_fmac_f32_e32 v97, v162, v96
	s_waitcnt lgkmcnt(3)
	v_pk_mul_f32 v[74:75], v[214:215], v[198:199]
	v_pk_mul_f32 v[76:77], v[162:163], v[200:201]
	s_waitcnt lgkmcnt(2)
	v_pk_mul_f32 v[78:79], v[218:219], v[202:203]
	v_pk_mul_f32 v[80:81], v[216:217], v[204:205]
	s_waitcnt lgkmcnt(1)
	v_mul_f32_e32 v36, v63, v207
	v_mul_f32_e32 v105, v61, v105
	v_mul_f32_e32 v107, v223, v107
	v_mul_f32_e32 v109, v221, v109
	v_mul_f32_e32 v115, v219, v115
	v_mul_f32_e32 v117, v217, v117
	v_mul_f32_e32 v121, v61, v121
	v_mul_f32_e32 v131, v219, v131
	v_mul_f32_e32 v133, v217, v133
	v_mul_f32_e32 v137, v61, v137
	v_mul_f32_e32 v147, v219, v147
	v_mul_f32_e32 v149, v217, v149
	v_mul_f32_e32 v153, v61, v153
	v_fmac_f32_e32 v224, v218, v82
	v_fmac_f32_e32 v225, v216, v84
	v_mul_f32_e32 v171, v219, v171
	v_mul_f32_e32 v173, v217, v173
	v_fmac_f32_e32 v87, v62, v86
	v_mul_f32_e32 v86, v61, v177
	v_mul_f32_e32 v177, v221, v181
	v_fmac_f32_e32 v93, v220, v92
	v_mul_f32_e32 v92, v219, v187
	v_mul_f32_e32 v181, v217, v189
	v_mul_f32_e32 v94, v61, v193
	s_waitcnt lgkmcnt(0)
; #define LAS __attribute__((address_space(3)))
; __device__ __forceinline__ float wave_sum(float v) {
; #pragma unroll
;     for (int o = 1; o < 64; o <<= 1) v += __shfl_xor(v, o);
;     return v;
; template <int LO, int HI> __global__ void __launch_bounds__(NWAVES * 64, 2) fox_fwd(Args args) {
;     ...
;             for (int q = 0; q < 8; ++q) { float a = 0.f;
; #pragma unroll
;                 for (int j = 0; j < 4; ++j) { const f32x4 w = *(const LAS f32x4*)(wf + q * 1024 + P1COL(j)); a += (v[j][0] * w[0] + v[j][1] * w[1]) + (v[j][2] * w[2] + v[j][3] * w[3]); }
;                 fl[q] = wave_sum(a); }
;             float mine = fl[0];
; #pragma unroll
;             for (int q = 1; q < 8; ++q) mine = (lane == q) ? fl[q] : mine;
	v_mul_f32_e32 v83, v222, v210
	v_fmac_f32_e32 v99, v218, v98
	v_fmac_f32_e32 v101, v216, v100
	v_mul_f32_e32 v82, v61, v209
	v_fmac_f32_e32 v103, v62, v102
	v_fmac_f32_e32 v111, v214, v110
	v_fmac_f32_e32 v113, v162, v112
	v_fmac_f32_e32 v119, v62, v118
	v_fmac_f32_e32 v127, v214, v126
	v_fmac_f32_e32 v129, v162, v128
	v_fmac_f32_e32 v135, v62, v134
	v_fmac_f32_e32 v143, v214, v142
	v_fmac_f32_e32 v145, v162, v144
	v_fmac_f32_e32 v151, v62, v150
	v_fmac_f32_e32 v159, v214, v158
	v_fmac_f32_e32 v161, v162, v160
	v_fmac_f32_e32 v175, v62, v174
	v_fmac_f32_e32 v179, v214, v182
	v_fmac_f32_e32 v90, v162, v184
	v_fmac_f32_e32 v183, v62, v190
	v_pk_mov_b32 v[84:85], v[74:75], v[76:77] op_sel:[1,0]
	v_mov_b32_e32 v75, v77
	v_pk_mov_b32 v[76:77], v[78:79], v[80:81] op_sel:[1,0]
	v_mov_b32_e32 v79, v81
	v_pk_fma_f32 v[62:63], v[62:63], v[206:207], v[36:37] op_sel_hi:[1,1,0]
	v_add_f32_e32 v36, v59, v67
	v_add_f32_e32 v81, v95, v97
	v_mul_f32_e32 v163, v220, v212
	v_mul_f32_e32 v185, v221, v213
	v_fmac_f32_e32 v105, v60, v104
	v_fmac_f32_e32 v107, v222, v106
	v_fmac_f32_e32 v109, v220, v108
	v_fmac_f32_e32 v115, v218, v114
	v_fmac_f32_e32 v117, v216, v116
	v_fmac_f32_e32 v121, v60, v120
	v_fmac_f32_e32 v131, v218, v130
	v_fmac_f32_e32 v133, v216, v132
	v_fmac_f32_e32 v137, v60, v136
	v_fmac_f32_e32 v147, v218, v146
	v_fmac_f32_e32 v149, v216, v148
	v_fmac_f32_e32 v153, v60, v152
	v_fmac_f32_e32 v171, v218, v170
	v_fmac_f32_e32 v173, v216, v172
	v_fmac_f32_e32 v86, v60, v176
	v_fmac_f32_e32 v92, v218, v186
	v_fmac_f32_e32 v181, v216, v188
	v_fmac_f32_e32 v94, v60, v192
	v_pk_fma_f32 v[60:61], v[60:61], v[208:209], v[82:83] op_sel_hi:[1,1,0]
	v_add_f32_e32 v59, v224, v225
	v_add_f32_e32 v80, v91, v93
	v_add_f32_e32 v82, v99, v101
	v_add_f32_e32 v91, v111, v113
	v_add_f32_e32 v98, v127, v129
	v_add_f32_e32 v102, v143, v145
	v_add_f32_e32 v106, v159, v161
	v_add_f32_e32 v90, v179, v90
	v_pk_add_f32 v[74:75], v[84:85], v[74:75]
	v_pk_add_f32 v[76:77], v[76:77], v[78:79]
	v_add_f32_e32 v36, 0, v36
	v_add_f32_e32 v78, 0, v81
	v_mul_f32_e32 v123, v223, v123
	v_mul_f32_e32 v125, v221, v125
	v_mul_f32_e32 v139, v223, v139
	v_mul_f32_e32 v141, v221, v141
	v_mul_f32_e32 v155, v223, v155
	v_mul_f32_e32 v157, v221, v157
	v_mul_f32_e32 v96, v223, v211
	v_mul_f32_e32 v187, v223, v195
	v_mul_f32_e32 v189, v221, v197
	v_add_f32_e32 v67, v87, v89
	v_add_f32_e32 v87, v103, v105
	v_add_f32_e32 v89, v107, v109
	v_add_f32_e32 v93, v115, v117
	v_add_f32_e32 v99, v131, v133
	v_add_f32_e32 v103, v147, v149
	v_add_f32_e32 v107, v171, v173
	v_add_f32_e32 v92, v92, v181
	v_mov_b32_e32 v63, v163
	v_mov_b32_e32 v61, v185
	v_add_f32_e32 v79, 0, v91
	v_add_f32_e32 v81, 0, v98
	v_add_f32_e32 v84, 0, v102
	v_add_f32_e32 v85, 0, v106
	v_add_f32_e32 v90, 0, v90
	v_add_f32_e32 v91, v74, v75
	v_pk_add_f32 v[74:75], v[76:77], v[76:77] op_sel:[0,1] op_sel_hi:[1,0]
	v_add_f32_e32 v36, v36, v59
	v_add_f32_e32 v59, v78, v82
	v_fmac_f32_e32 v123, v222, v122
	v_fmac_f32_e32 v125, v220, v124
	v_fmac_f32_e32 v139, v222, v138
	v_fmac_f32_e32 v141, v220, v140
	v_fmac_f32_e32 v155, v222, v154
	v_fmac_f32_e32 v157, v220, v156
	v_fmac_f32_e32 v88, v222, v178
	v_fmac_f32_e32 v177, v220, v180
	v_fmac_f32_e32 v187, v222, v194
	v_fmac_f32_e32 v189, v220, v196
	v_add_f32_e32 v95, v119, v121
	v_add_f32_e32 v100, v135, v137
	v_add_f32_e32 v104, v151, v153
	v_add_f32_e32 v86, v175, v86
	v_add_f32_e32 v94, v183, v94
	v_pk_add_f32 v[60:61], v[62:63], v[60:61]
	v_add_f32_e32 v62, v79, v93
	v_add_f32_e32 v63, v81, v99
	v_add_f32_e32 v76, v84, v103
	v_add_f32_e32 v77, v85, v107
	v_add_f32_e32 v78, v90, v92
	v_add_f32_e32 v82, 0, v91
	v_mov_b32_e32 v75, v96
	v_add_f32_e32 v36, v36, v67
	v_add_f32_e32 v59, v59, v87
	v_add_f32_e32 v97, v123, v125
	v_add_f32_e32 v101, v139, v141
	v_add_f32_e32 v105, v155, v157
	v_add_f32_e32 v88, v88, v177
	v_add_f32_e32 v108, v187, v189
	v_add_f32_e32 v67, v62, v95
	v_add_f32_e32 v79, v63, v100
	v_add_f32_e32 v76, v76, v104
	v_add_f32_e32 v77, v77, v86
	v_add_f32_e32 v78, v78, v94
	v_pk_add_f32 v[62:63], v[82:83], v[74:75]
	v_add_f32_e32 v36, v36, v80
	v_add_f32_e32 v59, v59, v89
	v_add_f32_e32 v67, v67, v97
	v_add_f32_e32 v74, v79, v101
	v_add_f32_e32 v75, v76, v105
	v_add_f32_e32 v76, v77, v88
	v_add_f32_e32 v77, v78, v108
	v_pk_add_f32 v[60:61], v[62:63], v[60:61]
	ds_bpermute_b32 v62, v165, v36
	ds_bpermute_b32 v63, v165, v59
	ds_bpermute_b32 v78, v165, v67
	ds_bpermute_b32 v79, v165, v74
	ds_bpermute_b32 v80, v165, v75
	ds_bpermute_b32 v81, v165, v76
	ds_bpermute_b32 v82, v165, v77
	v_add_f32_e32 v60, v60, v61
	s_waitcnt lgkmcnt(6)
	v_add_f32_e32 v36, v36, v62
	s_waitcnt lgkmcnt(5)
	v_add_f32_e32 v59, v59, v63
	ds_bpermute_b32 v61, v165, v60
	s_waitcnt lgkmcnt(5)
	v_add_f32_e32 v62, v67, v78
	s_waitcnt lgkmcnt(4)
	v_add_f32_e32 v63, v74, v79
	s_waitcnt lgkmcnt(3)
	v_add_f32_e32 v67, v75, v80
	s_waitcnt lgkmcnt(2)
	v_add_f32_e32 v74, v76, v81
	s_waitcnt lgkmcnt(1)
	v_add_f32_e32 v75, v77, v82
	ds_bpermute_b32 v76, v169, v36
	ds_bpermute_b32 v77, v169, v59
	ds_bpermute_b32 v78, v169, v62
	ds_bpermute_b32 v79, v169, v63
	ds_bpermute_b32 v80, v169, v67
	ds_bpermute_b32 v81, v169, v74
	ds_bpermute_b32 v82, v169, v75
	s_waitcnt lgkmcnt(7)
	v_add_f32_e32 v60, v60, v61
	s_waitcnt lgkmcnt(6)
	v_add_f32_e32 v36, v36, v76
	s_waitcnt lgkmcnt(5)
	v_add_f32_e32 v59, v59, v77
	ds_bpermute_b32 v61, v169, v60
	s_waitcnt lgkmcnt(5)
	v_add_f32_e32 v62, v62, v78
	ds_bpermute_b32 v76, v168, v36
	ds_bpermute_b32 v77, v168, v59
	s_waitcnt lgkmcnt(6)
	v_add_f32_e32 v63, v63, v79
	ds_bpermute_b32 v78, v168, v62
	s_waitcnt lgkmcnt(6)
	v_add_f32_e32 v67, v67, v80
	ds_bpermute_b32 v79, v168, v63
	s_waitcnt lgkmcnt(6)
; __device__ __forceinline__ float wave_sum(float v) {
; #pragma unroll
;     for (int o = 1; o < 64; o <<= 1) v += __shfl_xor(v, o);
;     return v;
; template <int LO, int HI> __global__ void __launch_bounds__(NWAVES * 64, 2) fox_fwd(Args args) {
;     ...
;                 fl[q] = wave_sum(a); }
;             float mine = fl[0];
; #pragma unroll
;             for (int q = 1; q < 8; ++q) mine = (lane == q) ? fl[q] : mine;
	v_add_f32_e32 v74, v74, v81
	ds_bpermute_b32 v80, v168, v67
	s_waitcnt lgkmcnt(6)
	v_add_f32_e32 v75, v75, v82
	ds_bpermute_b32 v81, v168, v74
	ds_bpermute_b32 v82, v168, v75
	s_waitcnt lgkmcnt(7)
	v_add_f32_e32 v60, v60, v61
	s_waitcnt lgkmcnt(6)
	v_add_f32_e32 v36, v36, v76
	s_waitcnt lgkmcnt(5)
	v_add_f32_e32 v59, v59, v77
	ds_bpermute_b32 v61, v168, v60
	s_waitcnt lgkmcnt(5)
	v_add_f32_e32 v62, v62, v78
	ds_bpermute_b32 v76, v167, v36
	ds_bpermute_b32 v77, v167, v59
	s_waitcnt lgkmcnt(6)
	v_add_f32_e32 v63, v63, v79
	ds_bpermute_b32 v78, v167, v62
	s_waitcnt lgkmcnt(6)
	v_add_f32_e32 v67, v67, v80
	ds_bpermute_b32 v79, v167, v63
	s_waitcnt lgkmcnt(6)
	v_add_f32_e32 v74, v74, v81
	ds_bpermute_b32 v80, v167, v67
	s_waitcnt lgkmcnt(6)
	v_add_f32_e32 v75, v75, v82
	ds_bpermute_b32 v81, v167, v74
	ds_bpermute_b32 v82, v167, v75
	s_waitcnt lgkmcnt(7)
	v_add_f32_e32 v60, v60, v61
	s_waitcnt lgkmcnt(6)
	v_add_f32_e32 v36, v36, v76
	s_waitcnt lgkmcnt(5)
	v_add_f32_e32 v59, v59, v77
	ds_bpermute_b32 v61, v167, v60
	s_waitcnt lgkmcnt(5)
	v_add_f32_e32 v62, v62, v78
	ds_bpermute_b32 v76, v166, v36
	ds_bpermute_b32 v77, v166, v59
	s_waitcnt lgkmcnt(6)
	v_add_f32_e32 v63, v63, v79
	ds_bpermute_b32 v78, v166, v62
	s_waitcnt lgkmcnt(6)
	v_add_f32_e32 v67, v67, v80
	ds_bpermute_b32 v79, v166, v63
	s_waitcnt lgkmcnt(6)
	v_add_f32_e32 v74, v74, v81
	ds_bpermute_b32 v80, v166, v67
	s_waitcnt lgkmcnt(6)
	v_add_f32_e32 v75, v75, v82
	ds_bpermute_b32 v81, v166, v74
	ds_bpermute_b32 v82, v166, v75
	s_waitcnt lgkmcnt(7)
	v_add_f32_e32 v60, v60, v61
	s_waitcnt lgkmcnt(6)
	v_add_f32_e32 v36, v36, v76
	s_waitcnt lgkmcnt(5)
	v_add_f32_e32 v59, v59, v77
	ds_bpermute_b32 v61, v166, v60
	s_waitcnt lgkmcnt(5)
	v_add_f32_e32 v62, v62, v78
	ds_bpermute_b32 v76, v164, v36
	ds_bpermute_b32 v77, v164, v59
	s_waitcnt lgkmcnt(6)
	v_add_f32_e32 v63, v63, v79
	ds_bpermute_b32 v78, v164, v62
	s_waitcnt lgkmcnt(6)
	v_add_f32_e32 v67, v67, v80
	ds_bpermute_b32 v79, v164, v63
	s_waitcnt lgkmcnt(6)
	v_add_f32_e32 v74, v74, v81
	ds_bpermute_b32 v80, v164, v67
	s_waitcnt lgkmcnt(6)
	v_add_f32_e32 v75, v75, v82
	ds_bpermute_b32 v81, v164, v74
	ds_bpermute_b32 v82, v164, v75
	s_waitcnt lgkmcnt(7)
	v_add_f32_e32 v60, v60, v61
	s_waitcnt lgkmcnt(6)
	v_add_f32_e32 v36, v36, v76
	s_waitcnt lgkmcnt(5)
	v_add_f32_e32 v59, v59, v77
	ds_bpermute_b32 v61, v164, v60
	s_waitcnt lgkmcnt(5)
	v_add_f32_e32 v62, v62, v78
	v_cndmask_b32_e64 v36, v36, v59, s[4:5]
	s_waitcnt lgkmcnt(4)
	v_add_f32_e32 v63, v63, v79
	v_cndmask_b32_e64 v36, v36, v62, s[6:7]
	s_waitcnt lgkmcnt(3)
	v_add_f32_e32 v67, v67, v80
	v_cndmask_b32_e64 v36, v36, v63, s[8:9]
	s_waitcnt lgkmcnt(2)
	v_add_f32_e32 v74, v74, v81
	v_cndmask_b32_e64 v36, v36, v67, s[10:11]
	s_waitcnt lgkmcnt(1)
	v_add_f32_e32 v75, v75, v82
	v_cndmask_b32_e64 v36, v36, v74, s[12:13]
	s_waitcnt lgkmcnt(0)
; template <int LO, int HI> __global__ void __launch_bounds__(NWAVES * 64, 2) fox_fwd(Args args) {
;     ...
;             { const float z = mine + bfv; const float ls = fminf(z, 0.f) - log1pf(__expf(-fabsf(z)));
; #pragma unroll
;               for (int k = 0; k < 4; ++k)
; #pragma unroll
;                   for (int e = 0; e < 4; ++e) lsq[k][e] = (r == 4 * k + e) ? ls : lsq[k][e]; }
;         }
;         if (lane < 8) { f32x4* dst = (f32x4*)(LF + (size_t)(b * 8 + lane) * T + (m0 - b * T));
; #pragma unroll
;             for (int k = 0; k < 4; ++k) dst[k] = lsq[k]; }
	v_add_f32_e32 v60, v60, v61
	v_cndmask_b32_e64 v36, v36, v75, s[14:15]
	v_cndmask_b32_e64 v36, v36, v60, s[16:17]
	v_add_f32_e32 v36, v71, v36
	v_min_f32_e32 v67, 0, v36
	v_mul_f32_e64 v36, |v36|, s29
	v_exp_f32_e32 v36, v36
	v_lshl_add_u64 v[56:57], v[56:57], 0, s[40:41]
	v_add_f32_e32 v59, 1.0, v36
	v_add_f32_e32 v62, -1.0, v59
	v_frexp_mant_f32_e32 v63, v59
	v_cvt_f64_f32_e32 v[60:61], v59
	v_sub_f32_e32 v74, v62, v59
	v_frexp_exp_i32_f64_e32 v60, v[60:61]
	v_cmp_gt_f32_e32 vcc, s37, v63
	v_sub_f32_e32 v62, v36, v62
	v_add_f32_e32 v61, 1.0, v74
	v_subbrev_co_u32_e32 v60, vcc, 0, v60, vcc
	v_add_f32_e32 v61, v62, v61
	v_sub_u32_e32 v62, 0, v60
	v_ldexp_f32 v59, v59, v62
	v_ldexp_f32 v61, v61, v62
	v_add_f32_e32 v62, -1.0, v59
	v_add_f32_e32 v74, 1.0, v59
	v_add_f32_e32 v63, 1.0, v62
	v_add_f32_e32 v75, -1.0, v74
	v_sub_f32_e32 v63, v59, v63
	v_sub_f32_e32 v59, v59, v75
	v_add_f32_e32 v59, v61, v59
	v_add_f32_e32 v75, v61, v63
	v_add_f32_e32 v61, v74, v59
	v_rcp_f32_e32 v78, v61
	v_add_f32_e32 v63, v62, v75
	v_sub_f32_e32 v74, v61, v74
	v_sub_f32_e32 v59, v59, v74
	v_mul_f32_e32 v80, v63, v78
	v_mul_f32_e32 v74, v61, v80
	v_fma_f32 v76, v80, v61, -v74
	v_sub_f32_e32 v62, v63, v62
	v_fmac_f32_e32 v76, v80, v59
	v_sub_f32_e32 v79, v75, v62
	v_add_f32_e32 v62, v74, v76
	v_sub_f32_e32 v75, v63, v62
	v_mov_b32_e32 v77, v62
	v_pk_add_f32 v[62:63], v[62:63], v[74:75] neg_lo:[0,1] neg_hi:[0,1]
	v_cvt_f32_i32_e32 v60, v60
	v_pk_add_f32 v[62:63], v[62:63], v[76:77] neg_lo:[0,1] neg_hi:[0,1]
	v_cmp_neq_f32_e32 vcc, s46, v36
	v_add_f32_e32 v63, v79, v63
	v_add_f32_e32 v62, v62, v63
	v_add_f32_e32 v63, v75, v62
	v_mul_f32_e32 v77, v78, v63
	v_mul_f32_e32 v74, v61, v77
	v_fma_f32 v76, v77, v61, -v74
	v_sub_f32_e32 v75, v75, v63
	v_fmac_f32_e32 v76, v77, v59
	v_add_f32_e32 v79, v62, v75
	v_add_f32_e32 v81, v80, v77
	v_add_f32_e32 v62, v74, v76
	v_sub_f32_e32 v61, v81, v80
	v_sub_f32_e32 v75, v63, v62
	v_sub_f32_e32 v59, v77, v61
	v_mov_b32_e32 v77, v62
	v_pk_add_f32 v[62:63], v[62:63], v[74:75] neg_lo:[0,1] neg_hi:[0,1]
	s_nop 0
	v_pk_add_f32 v[62:63], v[62:63], v[76:77] neg_lo:[0,1] neg_hi:[0,1]
	s_nop 0
	v_add_f32_e32 v61, v79, v63
	v_add_f32_e32 v61, v62, v61
	v_add_f32_e32 v61, v75, v61
	v_mul_f32_e32 v61, v78, v61
	v_add_f32_e32 v59, v59, v61
	v_add_f32_e32 v61, v81, v59
	v_mul_f32_e32 v62, v61, v61
	v_sub_f32_e32 v74, v61, v81
	v_fmamk_f32 v75, v62, 0x3e9b6dac, v20
	v_ldexp_f32 v63, v61, 1
	v_sub_f32_e32 v74, v59, v74
	v_mul_f32_e32 v61, v61, v62
	v_fmaak_f32 v59, v62, v75, 0x3f2aaada
	v_ldexp_f32 v77, v74, 1
	v_pk_mul_f32 v[74:75], v[60:61], v[58:59]
	s_nop 0
	v_fma_f32 v62, v60, s36, -v74
	v_fmac_f32_e32 v62, 0xb102e308, v60
	v_pk_add_f32 v[60:61], v[74:75], v[62:63]
	v_mov_b32_e32 v76, v74
	v_sub_f32_e32 v59, v61, v63
	v_sub_f32_e32 v59, v75, v59
	v_add_f32_e32 v77, v77, v59
	v_pk_add_f32 v[78:79], v[60:61], v[74:75] neg_lo:[0,1] neg_hi:[0,1]
	v_pk_add_f32 v[74:75], v[60:61], v[76:77]
	v_mov_b32_e32 v63, v60
	v_mov_b32_e32 v79, v75
	v_pk_add_f32 v[82:83], v[62:63], v[78:79] neg_lo:[0,1] neg_hi:[0,1]
	v_pk_add_f32 v[62:63], v[62:63], v[78:79]
	v_mov_b32_e32 v81, v60
	v_pk_add_f32 v[78:79], v[62:63], v[60:61] op_sel:[1,0] op_sel_hi:[0,1] neg_lo:[0,1] neg_hi:[0,1]
	v_mov_b32_e32 v80, v77
	v_mov_b32_e32 v76, v75
	v_mov_b32_e32 v77, v63
	v_pk_mov_b32 v[60:61], v[60:61], v[78:79] op_sel:[1,0]
	v_pk_add_f32 v[74:75], v[74:75], v[78:79] op_sel_hi:[1,0] neg_lo:[0,1] neg_hi:[0,1]
	v_pk_add_f32 v[60:61], v[76:77], v[60:61] neg_lo:[0,1] neg_hi:[0,1]
	v_mov_b32_e32 v74, v82
	v_pk_add_f32 v[60:61], v[80:81], v[60:61] neg_lo:[0,1] neg_hi:[0,1]
	v_mov_b32_e32 v83, v63
	v_pk_add_f32 v[74:75], v[74:75], v[60:61]
	s_nop 0
	v_pk_add_f32 v[76:77], v[74:75], v[74:75] op_sel:[0,1] op_sel_hi:[1,0]
	s_nop 0
	v_pk_add_f32 v[62:63], v[62:63], v[76:77] op_sel:[1,0] op_sel_hi:[0,1]
	v_mov_b32_e32 v75, v62
	v_mov_b32_e32 v61, v76
	v_pk_add_f32 v[76:77], v[74:75], v[82:83] neg_lo:[0,1] neg_hi:[0,1]
	s_nop 0
	v_sub_f32_e32 v59, v74, v76
	v_pk_add_f32 v[60:61], v[60:61], v[76:77] neg_lo:[0,1] neg_hi:[0,1]
	v_sub_f32_e32 v59, v82, v59
	v_add_f32_e32 v59, v60, v59
	v_add_f32_e32 v59, v59, v61
	v_add_f32_e32 v59, v62, v59
	v_cndmask_b32_e32 v59, v64, v59, vcc
	v_cmp_ngt_f32_e32 vcc, -1.0, v36
	s_nop 1
	v_cndmask_b32_e32 v59, v65, v59, vcc
	v_cmp_neq_f32_e32 vcc, -1.0, v36
	s_nop 1
	v_cndmask_b32_e32 v59, v66, v59, vcc
	v_cmp_lt_f32_e64 vcc, |v36|, s47
	s_nop 1
	v_cndmask_b32_e32 v36, v59, v36, vcc
	v_sub_f32_e32 v36, v67, v36
	s_cselect_b64 vcc, -1, 0
	s_cmpk_eq_i32 s30, 0x1000
	v_cndmask_b32_e32 v37, v37, v36, vcc
	s_cselect_b64 vcc, -1, 0
	s_cmpk_eq_i32 s30, 0x2000
	v_cndmask_b32_e32 v21, v21, v36, vcc
	s_cselect_b64 vcc, -1, 0
	s_cmpk_eq_i32 s30, 0x3000
	v_cndmask_b32_e32 v30, v30, v36, vcc
	s_cselect_b64 vcc, -1, 0
	s_cmpk_eq_i32 s30, 0x4000
	v_cndmask_b32_e32 v31, v31, v36, vcc
	s_cselect_b64 vcc, -1, 0
	s_cmpk_eq_i32 s30, 0x5000
	v_cndmask_b32_e32 v32, v32, v36, vcc
	s_cselect_b64 vcc, -1, 0
	s_cmpk_eq_i32 s30, 0x6000
	v_cndmask_b32_e32 v33, v33, v36, vcc
	s_cselect_b64 vcc, -1, 0
	s_cmpk_eq_i32 s30, 0x7000
	v_cndmask_b32_e32 v26, v26, v36, vcc
	s_cselect_b64 vcc, -1, 0
	s_cmpk_eq_u32 s30, 0x8000
	v_cndmask_b32_e32 v27, v27, v36, vcc
	s_cselect_b64 vcc, -1, 0
	s_cmpk_eq_u32 s30, 0x9000
	v_cndmask_b32_e32 v28, v28, v36, vcc
	s_cselect_b64 vcc, -1, 0
	s_cmpk_eq_u32 s30, 0xa000
	v_cndmask_b32_e32 v29, v29, v36, vcc
	s_cselect_b64 vcc, -1, 0
	s_cmpk_eq_u32 s30, 0xb000
	v_cndmask_b32_e32 v22, v22, v36, vcc
	s_cselect_b64 vcc, -1, 0
	s_cmpk_eq_u32 s30, 0xc000
	v_cndmask_b32_e32 v23, v23, v36, vcc
	s_cselect_b64 vcc, -1, 0
	s_cmpk_eq_u32 s30, 0xd000
	v_cndmask_b32_e32 v24, v24, v36, vcc
	s_cselect_b64 vcc, -1, 0
	s_add_u32 s30, s30, 0x1000
	s_addc_u32 s31, s31, 0
	s_cmpk_eq_u32 s30, 0xe000
	v_cndmask_b32_e32 v25, v25, v36, vcc
	s_cbranch_scc0 .LBB0_131
	v_cmp_gt_u32_e32 vcc, 8, v1
	s_and_saveexec_b64 s[4:5], vcc
	s_cbranch_execz .LBB0_134
	v_lshl_or_b32 v2, s44, 3, v1
	v_ashrrev_i32_e32 v3, 31, v2
	s_lshl_b32 s6, s44, 12
	v_lshlrev_b64 v[2:3], 14, v[2:3]
	s_sub_i32 s6, s28, s6
	v_lshl_add_u64 v[2:3], s[26:27], 0, v[2:3]
	s_ashr_i32 s7, s6, 31
	v_lshl_add_u64 v[2:3], s[6:7], 2, v[2:3]
	s_mov_b64 s[6:7], 0x100000
	v_lshl_add_u64 v[4:5], v[2:3], 0, s[6:7]
	v_add_co_u32_e32 v2, vcc, 0x100000, v2
	v_mov_b32_e32 v20, v37
	s_nop 0
	v_addc_co_u32_e32 v3, vcc, 0, v3, vcc
	global_store_dwordx4 v[2:3], v[18:21], off
	global_store_dwordx4 v[4:5], v[30:33], off offset:16
	global_store_dwordx4 v[4:5], v[26:29], off offset:32
	global_store_dwordx4 v[4:5], v[22:25], off offset:48
